# barrier early L1 invalidate + K-tile LDS swizzle bit (conflict-free ds_read_b128) + cvt tile loads issued together
# speedup vs baseline: 1.0121x; 1.0095x over previous
; __device__ __forceinline__ int tid_opaque() { int t = (int)threadIdx.x; asm volatile("" : "+v"(t)); return t; }
; __device__ __forceinline__ int v_st(int k, int c) { const int kk = (k & ~0xC) | ((k & 4) << 1) | ((k & 8) >> 1); return ((kk >> 3) * 4 + (c >> 5)) * 512 + ((kk & 7) * 32 + (c & 31)) * 2; }
; __device__ __forceinline__ int v_rd_base(int lane) { return ((lane & 3) << 3) | (((lane >> 2) & 3) << 6) | (((lane >> 4) & 1) << 5) | (((lane >> 5) & 1) << 8); }
; #define SLOAD(i, k0) do { sv0[i] = *reinterpret_cast<const bf16x8*>(&Vh[(size_t)((k0) + sr) * LDQ + sc]); sv1[i] = *reinterpret_cast<const bf16x8*>(&Vh[(size_t)((k0) + 32 + sr) * LDQ + sc]); \
;     sk0[i] = *reinterpret_cast<const bf16x8*>(&Kh[(size_t)((k0) + kr) * LDQ + kc]); } while (0)
; #define SWAIT() asm volatile("s_waitcnt vmcnt(3)" ::: "memory")
; __device__ __forceinline__ void attn_unit(const bf16_t* __restrict__ Qb, const bf16_t* __restrict__ Kh, const bf16_t* __restrict__ Vh, bf16_t* __restrict__ Ob, int qpos0, float slope2, char* lds, const int NT) {
;     const int tid = tid_opaque(), wid = tid >> 6, lane = tid & 63, r32 = lane & 31, hi = lane >> 5;
;     char* V_lds = lds; char* K_lds = lds + 2 * SHM_V;
;     float* wsf = (float*)(lds + 2 * SHM_V + 2 * SHM_K) + wid * 64; float* li_l = wsf; float* al_l = wsf + 32;
;     float m_reg = -1e30f, l_reg = 0; f32x16 o[4] = {}; bf16x8 qr[4];
;     const bf16_t* Qw = Qb + (size_t)(wid * QBLK + r32) * LDQ + hi * 8;
; #pragma unroll
;     for (int d0 = 0; d0 < 4; ++d0) qr[d0] = *reinterpret_cast<const bf16x8*>(Qw + d0 * 16);
;     const float qposf = (float)(qpos0 + wid * QBLK + r32);
;     const int sr = tid >> 4, sc = (tid & 15) * 8, vst0 = v_st(sr, sc), vst1 = v_st(32 + sr, sc);
;     const int kr = tid >> 3, kc = (tid & 7) * 8, kst = KSWZ(kr, kc * 2);
;     const int vb0 = (int)(uintptr_t)V_lds + v_rd_base(lane);
;     bf16x8 sv0[2], sv1[2], sk0[2];
;     ...
;     f32x16 pA0, pA1, pB0, pB1; float mnA, mnB, alA, alB; bf16x8 pa0, pa1, pa2, pa3;
;     __syncthreads();
;     SLOAD(0, 0); asm volatile("s_waitcnt vmcnt(0)" ::: "memory"); SWRITE(0, 0); __syncthreads();
;     qkt(pA0, pA1, K_lds, qr, r32, hi); partialSM(pA0, pA1, m_reg, mnA, alA, qposf, slope2, hi);
;     SLOAD(1, KVBLK); if (2 < NT) SLOAD(0, 2 * KVBLK);
;     SWAIT(); SWRITE(1, 1); __syncthreads();
.LBB0_152:
	s_or_b64 exec, exec, s[0:1]
	v_lshlrev_b32_e32 v2, 7, v203
	v_ashrrev_i32_e32 v81, 31, v80
	v_and_b32_e32 v112, 0x2000, v2
	v_lshlrev_b64 v[2:3], 6, v[80:81]
	s_movk_i32 s0, 0x180
	v_lshl_add_u64 v[2:3], v[2:3], 0, v[112:113]
	v_mov_b64_e32 v[4:5], s[64:65]
	s_movk_i32 s2, 0xc00
	v_or_b32_e32 v205, v112, v0
	v_bitop3_b32 v8, v203, s0, v203 bitop3:0xc
	v_mad_u64_u32 v[6:7], s[0:1], v2, s2, v[4:5]
	v_bfe_u32 v169, v203, 5, 1
	v_mad_i32_i24 v7, v3, s2, v7
	v_mad_u64_u32 v[2:3], s[0:1], v205, s2, v[4:5]
	v_lshlrev_b32_e32 v166, 1, v8
	v_mov_b32_e32 v167, v113
	v_lshlrev_b32_e32 v4, 6, v80
	v_mov_b32_e32 v81, v154
	v_lshl_add_u64 v[2:3], v[2:3], 0, v[166:167]
	v_lshlrev_b32_e32 v112, 7, v169
	v_sub_u32_e32 v4, v0, v4
	s_movk_i32 s0, 0xffe0
	v_ashrrev_i32_e32 v0, 1, v81
	v_lshl_add_u64 v[2:3], v[2:3], 0, v[112:113]
	v_bfe_u32 v206, v81, 5, 1
	v_and_b32_e32 v168, 0xffffffe0, v0
	v_bfi_b32 v0, s0, v0, v81
	v_sub_u32_e32 v207, v1, v80
	v_mad_i64_i32 v[0:1], s[0:1], v0, s2, v[2:3]
	v_lshlrev_b32_e32 v38, 4, v206
	v_mov_b32_e32 v39, v113
	v_and_b32_e32 v204, 31, v81
	v_lshl_add_u64 v[0:1], v[0:1], 0, v[38:39]
	global_load_dwordx4 v[126:129], v[0:1], off
	global_load_dwordx4 v[122:125], v[0:1], off offset:32
	global_load_dwordx4 v[118:121], v[0:1], off offset:64
	global_load_dwordx4 v[114:117], v[0:1], off offset:96
	v_or_b32_e32 v0, v204, v4
	v_ashrrev_i32_e32 v82, 4, v81
	v_add_u32_e32 v0, v0, v168
	v_and_b32_e32 v1, 0xfffff0, v82
	v_lshlrev_b32_e32 v3, 1, v82
	v_cvt_f32_i32_e32 v208, v0
	v_lshlrev_b32_e32 v0, 3, v81
	v_and_or_b32 v1, v3, 8, v1
	v_lshrrev_b32_e32 v3, 1, v82
	v_lshrrev_b32_e32 v1, 1, v1
	v_bfe_u32 v4, v0, 5, 2
	v_and_b32_e32 v5, 3, v82
	v_or_b32_e32 v1, v1, v4
	v_and_or_b32 v3, v3, 4, v5
	v_lshlrev_b32_e32 v5, 4, v81
	v_lshl_add_u64 v[34:35], v[6:7], 0, v[166:167]
	v_lshlrev_b32_e32 v1, 9, v1
	v_lshlrev_b32_e32 v3, 6, v3
	v_and_b32_e32 v6, 48, v5
	v_add_u32_e32 v8, 32, v82
	v_or3_b32 v7, v1, v3, v6
	v_and_b32_e32 v1, 0xfffff0, v8
	v_lshlrev_b32_e32 v9, 1, v8
	v_and_or_b32 v1, v9, 8, v1
	v_lshrrev_b32_e32 v1, 1, v1
	v_and_b32_e32 v2, 0x78, v0
	v_or_b32_e32 v1, v1, v4
	v_ashrrev_i32_e32 v83, 3, v81
	v_and_b32_e32 v0, 56, v0
	v_lshlrev_b32_e32 v1, 9, v1
	v_lshlrev_b32_e32 v36, 1, v0
	v_lshlrev_b32_e32 v0, 4, v83
	v_or3_b32 v3, v1, v3, v6
	v_lshlrev_b32_e32 v1, 7, v83
	v_and_b32_e32 v0, 0x70, v0
	v_and_b32_e32 v219, 16, v83
	v_xor_b32_e32 v0, v0, v219
	v_lshl_add_u64 v[32:33], v[34:35], 0, v[112:113]
	v_bitop3_b32 v4, v36, v1, v0 bitop3:0xde
	v_mad_i64_i32 v[0:1], s[0:1], v82, s2, v[34:35]
	v_lshlrev_b32_e32 v112, 1, v2
	v_lshl_add_u64 v[0:1], v[0:1], 0, v[112:113]
	s_barrier
	global_load_dwordx4 v[130:133], v[0:1], off offset:2048
	v_mad_i64_i32 v[0:1], s[0:1], v8, s2, v[34:35]
	v_lshl_add_u64 v[0:1], v[0:1], 0, v[112:113]
	global_load_dwordx4 v[134:137], v[0:1], off offset:2048
	v_mad_i64_i32 v[0:1], s[0:1], v83, s2, v[32:33]
	v_mov_b32_e32 v37, v113
	v_lshl_add_u64 v[0:1], v[0:1], 0, v[36:37]
	global_load_dwordx4 v[138:141], v[0:1], off offset:1024
	v_lshlrev_b32_e32 v39, 7, v204
	v_and_b32_e32 v48, 0x70, v5
	v_and_b32_e32 v219, 16, v204
	v_xor_b32_e32 v48, v48, v219
	v_bitop3_b32 v0, v38, v39, v48 bitop3:0xde
	v_add_u32_e32 v219, 0, v7
	v_add_u32_e32 v220, 0, v3
	v_add_u32_e32 v221, 0, v4
	v_add_u32_e32 v215, 0, v0
	s_waitcnt vmcnt(0)
	v_or_b32_e32 v40, 32, v38
	v_bitop3_b32 v40, v40, v39, v48 bitop3:0xde
	v_add_u32_e32 v214, 0, v40
	v_cmp_lt_i32_e64 s[6:7], 2, v207
	s_waitcnt vmcnt(2)
	ds_write_b128 v219, v[130:133]
	s_waitcnt vmcnt(1)
	ds_write_b128 v220, v[134:137]
	s_waitcnt vmcnt(0)
	ds_write_b128 v221, v[138:141] offset:32768
	s_waitcnt lgkmcnt(0)
	s_barrier
; __device__ __forceinline__ void partialSM(f32x16& p0, f32x16& p1, float& m_reg, float& mn, float& alpha, float dq, float slope2, int hi) {
;     const float d0 = dq - (float)(4 * hi);
; #pragma unroll
;     for (int r = 0; r < 16; ++r) { const float c = (float)((r & 3) + 8 * (r >> 2)); p0[r] = fmaf(-slope2, fabsf(d0 - c), p0[r]); p1[r] = fmaf(-slope2, fabsf(d0 - c - 32.0f), p1[r]); }
;     float pmax = p0[0];
; #pragma unroll
;     for (int r = 1; r < 16; ++r) pmax = fmaxf(pmax, p0[r]);
; #pragma unroll
;     for (int r = 0; r < 16; ++r) pmax = fmaxf(pmax, p1[r]);
;     { auto rr = __builtin_amdgcn_permlane32_swap(__float_as_uint(pmax), __float_as_uint(pmax), false, false); pmax = fmaxf(__uint_as_float(rr[0]), __uint_as_float(rr[1])); }
;     if (__builtin_expect(__all(pmax - m_reg <= THR), 1)) { mn = m_reg; alpha = 1.f; }
;     else { mn = fmaxf(m_reg, pmax); alpha = __builtin_amdgcn_exp2f(m_reg - mn); m_reg = mn; }
; #pragma unroll
;     for (int r = 0; r < 16; ++r) { p0[r] = p0[r] - mn; p1[r] = p1[r] - mn; }
; #pragma unroll
;     for (int r = 0; r < 16; ++r) p0[r] = __builtin_amdgcn_exp2f(p0[r]);
; }
; __device__ __forceinline__ void qkt(f32x16& p0, f32x16& p1, const char* Ks, const bf16x8* qr, int r32, int hi) {
;     p0 = f32x16{}; p1 = f32x16{};
; #pragma unroll
;     for (int d0 = 0; d0 < 4; ++d0) { const int cb = (d0 * 16 + hi * 8) * 2;
;         const bf16x8 b0 = *reinterpret_cast<const bf16x8*>(Ks + KSWZ(r32, cb));
;         const bf16x8 b1 = *reinterpret_cast<const bf16x8*>(Ks + KSWZ(32 + r32, cb));
;         p0 = __builtin_amdgcn_mfma_f32_32x32x16_bf16(b0, qr[d0], p0, 0, 0, 0);
;         p1 = __builtin_amdgcn_mfma_f32_32x32x16_bf16(b1, qr[d0], p1, 0, 0, 0); }
; }
	ds_read_b128 v[0:3], v215 offset:32768
	ds_read_b128 v[4:7], v215 offset:36864
	s_waitcnt lgkmcnt(1)
	v_mfma_f32_32x32x16_bf16 v[16:31], v[0:3], v[126:129], 0
	ds_read_b128 v[40:43], v214 offset:32768
	ds_read_b128 v[44:47], v214 offset:36864
	s_waitcnt lgkmcnt(2)
	v_mfma_f32_32x32x16_bf16 v[0:15], v[4:7], v[126:129], 0
	s_waitcnt lgkmcnt(1)
	v_mfma_f32_32x32x16_bf16 v[16:31], v[40:43], v[122:125], v[16:31]
	v_or_b32_e32 v40, 64, v38
	v_bitop3_b32 v40, v40, v39, v48 bitop3:0xde
	v_add_u32_e32 v216, 0, v40
	v_or_b32_e32 v38, 0x60, v38
	v_bitop3_b32 v38, v38, v39, v48 bitop3:0xde
	v_add_u32_e32 v217, 0, v38
	s_waitcnt lgkmcnt(0)
	v_mfma_f32_32x32x16_bf16 v[0:15], v[44:47], v[122:125], v[0:15]
	ds_read_b128 v[40:43], v216 offset:32768
	ds_read_b128 v[44:47], v216 offset:36864
	s_waitcnt lgkmcnt(1)
	v_mfma_f32_32x32x16_bf16 v[16:31], v[40:43], v[118:121], v[16:31]
	s_waitcnt lgkmcnt(0)
	v_mfma_f32_32x32x16_bf16 v[0:15], v[44:47], v[118:121], v[0:15]
	ds_read_b128 v[38:41], v217 offset:32768
	ds_read_b128 v[42:45], v217 offset:36864
	s_waitcnt lgkmcnt(1)
	v_mfma_f32_32x32x16_bf16 v[16:31], v[38:41], v[114:117], v[16:31]
	v_lshlrev_b32_e32 v38, 2, v206
	v_cvt_f32_ubyte0_e32 v209, v38
	v_sub_f32_e32 v52, v208, v209
	v_add_f32_e32 v53, -1.0, v52
	s_waitcnt lgkmcnt(0)
	v_mfma_f32_32x32x16_bf16 v[0:15], v[42:45], v[114:117], v[0:15]
	s_nop 5
	v_fma_f32 v39, -v170, |v52|, v16
	v_fma_f32 v40, -v170, |v53|, v17
	v_add_f32_e64 v16, v52, s72
	v_add_f32_e64 v17, v53, s72
	v_max_f32_e32 v43, v39, v40
	v_and_b32_e32 v17, 0x7fffffff, v17
	v_and_b32_e32 v16, 0x7fffffff, v16
	v_pk_fma_f32 v[16:17], v[170:171], v[16:17], v[0:1] op_sel_hi:[0,1,1] neg_lo:[1,0,0] neg_hi:[1,0,0]
	v_pk_add_f32 v[0:1], v[52:53], s[38:39] op_sel_hi:[0,1]
	v_fma_f32 v41, -v170, |v0|, v18
	v_fma_f32 v42, -v170, |v1|, v19
	v_pk_add_f32 v[0:1], v[0:1], s[72:73] op_sel_hi:[1,0]
	s_nop 0
	v_and_b32_e32 v1, 0x7fffffff, v1
	v_and_b32_e32 v0, 0x7fffffff, v0
	v_pk_fma_f32 v[18:19], v[170:171], v[0:1], v[2:3] op_sel_hi:[0,1,1] neg_lo:[1,0,0] neg_hi:[1,0,0]
	v_pk_add_f32 v[0:1], v[52:53], s[30:31] op_sel_hi:[0,1]
	v_max3_f32 v2, v43, v41, v42
	v_fma_f32 v43, -v170, |v0|, v20
	v_fma_f32 v44, -v170, |v1|, v21
	v_pk_add_f32 v[0:1], v[0:1], s[72:73] op_sel_hi:[1,0]
	v_max3_f32 v2, v2, v43, v44
	v_and_b32_e32 v1, 0x7fffffff, v1
	v_and_b32_e32 v0, 0x7fffffff, v0
	v_pk_fma_f32 v[20:21], v[170:171], v[0:1], v[4:5] op_sel_hi:[0,1,1] neg_lo:[1,0,0] neg_hi:[1,0,0]
	v_pk_add_f32 v[0:1], v[52:53], s[62:63] op_sel_hi:[0,1]
	v_fma_f32 v45, -v170, |v0|, v22
	v_fma_f32 v46, -v170, |v1|, v23
	v_pk_add_f32 v[0:1], v[0:1], s[72:73] op_sel_hi:[1,0]
	v_max3_f32 v2, v2, v45, v46
	v_and_b32_e32 v1, 0x7fffffff, v1
	v_and_b32_e32 v0, 0x7fffffff, v0
	v_pk_fma_f32 v[22:23], v[170:171], v[0:1], v[6:7] op_sel_hi:[0,1,1] neg_lo:[1,0,0] neg_hi:[1,0,0]
	v_pk_add_f32 v[0:1], v[52:53], s[40:41] op_sel_hi:[0,1]
	v_fma_f32 v47, -v170, |v0|, v24
	v_fma_f32 v48, -v170, |v1|, v25
	v_pk_add_f32 v[0:1], v[0:1], s[72:73] op_sel_hi:[1,0]
	v_max3_f32 v2, v2, v47, v48
	v_and_b32_e32 v1, 0x7fffffff, v1
	v_and_b32_e32 v0, 0x7fffffff, v0
	v_pk_fma_f32 v[24:25], v[170:171], v[0:1], v[8:9] op_sel_hi:[0,1,1] neg_lo:[1,0,0] neg_hi:[1,0,0]
	v_pk_add_f32 v[0:1], v[52:53], s[42:43] op_sel_hi:[0,1]
	v_fma_f32 v49, -v170, |v0|, v26
	v_fma_f32 v50, -v170, |v1|, v27
	v_pk_add_f32 v[0:1], v[0:1], s[72:73] op_sel_hi:[1,0]
	v_max3_f32 v2, v2, v49, v50
	v_and_b32_e32 v1, 0x7fffffff, v1
	v_and_b32_e32 v0, 0x7fffffff, v0
	v_pk_fma_f32 v[26:27], v[170:171], v[0:1], v[10:11] op_sel_hi:[0,1,1] neg_lo:[1,0,0] neg_hi:[1,0,0]
	v_pk_add_f32 v[0:1], v[52:53], s[44:45] op_sel_hi:[0,1]
	v_fma_f32 v28, -v170, |v0|, v28
	v_fma_f32 v29, -v170, |v1|, v29
	v_pk_add_f32 v[0:1], v[0:1], s[72:73] op_sel_hi:[1,0]
	v_max3_f32 v2, v2, v28, v29
	v_and_b32_e32 v1, 0x7fffffff, v1
	v_and_b32_e32 v0, 0x7fffffff, v0
	v_pk_fma_f32 v[12:13], v[170:171], v[0:1], v[12:13] op_sel_hi:[0,1,1] neg_lo:[1,0,0] neg_hi:[1,0,0]
	v_pk_add_f32 v[0:1], v[52:53], s[48:49] op_sel_hi:[0,1]
	v_fma_f32 v30, -v170, |v0|, v30
	v_fma_f32 v31, -v170, |v1|, v31
	v_pk_add_f32 v[0:1], v[0:1], s[72:73] op_sel_hi:[1,0]
	v_add_u32_e32 v4, 0x60, v82
	v_and_b32_e32 v1, 0x7fffffff, v1
	v_and_b32_e32 v0, 0x7fffffff, v0
	v_pk_fma_f32 v[14:15], v[170:171], v[0:1], v[14:15] op_sel_hi:[0,1,1] neg_lo:[1,0,0] neg_hi:[1,0,0]
	v_max3_f32 v0, v2, v30, v31
	v_max3_f32 v0, v0, v16, v17
	v_max3_f32 v0, v0, v18, v19
	v_max3_f32 v0, v0, v20, v21
	v_max3_f32 v0, v0, v22, v23
	v_max3_f32 v0, v0, v24, v25
	v_max3_f32 v0, v0, v26, v27
	v_max3_f32 v0, v0, v12, v13
	v_max3_f32 v0, v0, v14, v15
	v_mov_b32_e32 v1, v0
	s_nop 1
	v_permlane32_swap_b32_e32 v0, v1
	v_max_f32_e32 v1, v1, v1
	v_max_f32_e32 v0, v0, v0
	v_max_f32_e32 v51, v0, v1
	v_add_f32_e32 v0, 0x7149f2ca, v51
	v_cmp_ge_f32_e32 vcc, s68, v0
	v_add_u32_e32 v0, 64, v82
	v_add_u32_e32 v8, 64, v83
	v_mad_i64_i32 v[0:1], s[0:1], v0, s2, v[34:35]
	v_mad_i64_i32 v[4:5], s[0:1], v4, s2, v[34:35]
	v_mad_i64_i32 v[8:9], s[0:1], v8, s2, v[32:33]
	v_lshl_add_u64 v[0:1], v[0:1], 0, v[112:113]
	v_lshl_add_u64 v[4:5], v[4:5], 0, v[112:113]
	v_lshl_add_u64 v[8:9], v[8:9], 0, v[36:37]
	global_load_dwordx4 v[0:3], v[0:1], off offset:2048
	s_cmp_eq_u64 vcc, exec
	global_load_dwordx4 v[4:7], v[4:5], off offset:2048
	s_cselect_b64 vcc, -1, 0
	global_load_dwordx4 v[8:11], v[8:9], off offset:1024
	s_and_saveexec_b64 s[0:1], s[6:7]
	s_cbranch_execz .LBB0_154
	v_add_u32_e32 v52, 0x80, v82
	s_movk_i32 s8, 0xc00
	v_add_u32_e32 v54, 0xa0, v82
	v_mad_i64_i32 v[52:53], s[2:3], v52, s8, v[34:35]
	v_mad_i64_i32 v[34:35], s[2:3], v54, s8, v[34:35]
	v_lshl_add_u64 v[52:53], v[52:53], 0, v[112:113]
	v_lshl_add_u64 v[34:35], v[34:35], 0, v[112:113]
	global_load_dwordx4 v[130:133], v[52:53], off offset:2048
	global_load_dwordx4 v[134:137], v[34:35], off offset:2048
	v_add_u32_e32 v34, 0x80, v83
	v_mad_i64_i32 v[32:33], s[2:3], v34, s8, v[32:33]
	v_lshl_add_u64 v[32:33], v[32:33], 0, v[36:37]
	global_load_dwordx4 v[138:141], v[32:33], off offset:1024

; __device__ __forceinline__ unsigned short f2bf(float f) { return (unsigned short)(pk2(f, 0.f) & 0xffffu); }
; __device__ __forceinline__ void cvt_tile(unsigned char* lds, const float* src, int ld, int n_begin, int K, bf16_t* dst, int Kd, int koff, int mode, int roff, int t, int tid) {
;     const int ntk = Kd / 64; unsigned short* tile = (unsigned short*)lds;
;     const int tn = t / ntk, tk = t - tn * ntk; const int n0 = tn * 64, k0 = tk * 64;
;     const bool valid = (src != nullptr) && (k0 >= koff) && (k0 < koff + K);
;     __syncthreads();
;     if (valid) {
; #pragma unroll
;         for (int it = 0; it < 2; ++it) { const int idx = tid + 512 * it, kr = idx >> 4, nc4 = idx & 15;
;             const f32x4 v = *(const f32x4*)(src + (size_t)(k0 - koff + kr) * ld + n_begin + n0 + 4 * nc4);
; #pragma unroll
;             for (int j = 0; j < 4; ++j) tile[(4 * nc4 + j) * 66 + kr] = f2bf(v[j]); }
;     }
; __device__ __forceinline__ void cvt_ffn_tile(unsigned char* lds, unsigned char* ws, const float* w_in, const float* w_out, int gt, int tid) {
;     bf16_t* WA = (bf16_t*)(ws + WS_WA); bf16_t* WB = (bf16_t*)(ws + WS_WB);
;     if (gt < 704) cvt_tile(lds, w_in, NFF, 0, DM, WA, DM, 0, 1, 0, gt, tid);
;     else if (gt < 1408) cvt_tile(lds, w_in, NFF, DFF, DM, WA, DM, 0, 1, 128, gt - 704, tid);
;     else cvt_tile(lds, w_out, DM, 0, DFF, WB, DFF, 0, 0, 0, gt - 1408, tid);
.LBB0_175:
	s_or_b64 exec, exec, s[18:19]
	s_and_b64 s[0:1], exec, s[0:1]
	s_or_b64 s[16:17], s[0:1], s[16:17]
	s_andn2_b64 exec, exec, s[16:17]
	s_cbranch_execnz .LBB0_141
	s_or_b64 exec, exec, s[16:17]
	v_add_u32_e32 v12, 0xfffffe00, v203
	s_movk_i32 s0, 0x108
	v_cmp_gt_u32_e32 vcc, s0, v12
	s_mov_b64 s[0:1], -1
	s_and_saveexec_b64 s[8:9], vcc
	s_cbranch_execz .LBB0_140
	s_movk_i32 s0, 0x57
	v_lshlrev_b32_e32 v13, 3, v12
	v_cmp_lt_u32_e32 vcc, s0, v12
	s_and_saveexec_b64 s[0:1], vcc
	s_xor_b64 s[0:1], exec, s[0:1]
	s_cbranch_execz .LBB0_191
	s_movk_i32 s2, 0xaf
	v_cmp_lt_u32_e64 s[6:7], s2, v12
	s_and_saveexec_b64 s[2:3], s[6:7]
	s_xor_b64 s[10:11], exec, s[2:3]
	s_cbranch_execz .LBB0_184
	v_add_u32_e32 v0, 0xfffffa80, v13
	v_mul_u32_u24_e32 v1, 0xba2f, v0
	v_lshrrev_b32_e32 v1, 21, v1
	s_movk_i32 s2, 0xffd4
	v_mad_i32_i24 v0, v1, s2, v0
	v_cmp_gt_u32_e64 s[6:7], 44, v0
	v_lshlrev_b32_e32 v5, 6, v1
	v_lshlrev_b32_e32 v4, 6, v0
	s_and_b64 s[6:7], s[28:29], s[6:7]
	s_waitcnt vmcnt(63) expcnt(7) lgkmcnt(15)
	s_barrier
	s_and_saveexec_b64 s[16:17], s[6:7]
	s_cbranch_execz .LBB0_181
	v_add_u32_e32 v0, v4, v171
	v_lshlrev_b32_e32 v112, 2, v5
	v_ashrrev_i32_e32 v1, 31, v0
	v_lshl_add_u64 v[6:7], v[160:161], 0, v[112:113]
	v_lshlrev_b64 v[0:1], 12, v[0:1]
	v_lshl_add_u64 v[0:1], v[6:7], 0, v[0:1]
	global_load_dwordx4 v[0:3], v[0:1], off
	v_add_u32_e32 v64, v4, v199
	v_ashrrev_i32_e32 v65, 31, v64
	v_lshlrev_b64 v[64:65], 12, v[64:65]
	v_lshl_add_u64 v[64:65], v[6:7], 0, v[64:65]
	global_load_dwordx4 v[64:67], v[64:65], off
	v_add_u32_e32 v8, v197, v198
	s_waitcnt vmcnt(1)
	v_cvt_pk_bf16_f32 v0, v0, s0
	ds_write_b16 v8, v0
	v_cvt_pk_bf16_f32 v0, v1, s0
	ds_write_b16 v8, v0 offset:132
	v_cvt_pk_bf16_f32 v0, v2, s0
	ds_write_b16 v8, v0 offset:264
	v_cvt_pk_bf16_f32 v0, v3, s0
	ds_write_b16 v8, v0 offset:396
	v_add_u32_e32 v6, v200, v198
	s_waitcnt vmcnt(0)
	v_cvt_pk_bf16_f32 v0, v64, s0
	ds_write_b16 v6, v0
	v_cvt_pk_bf16_f32 v0, v65, s0
	ds_write_b16 v6, v0 offset:132
	v_cvt_pk_bf16_f32 v0, v66, s0
	ds_write_b16 v6, v0 offset:264
	v_cvt_pk_bf16_f32 v0, v67, s0
	ds_write_b16 v6, v0 offset:396

; __device__ __forceinline__ unsigned short f2bf(float f) { return (unsigned short)(pk2(f, 0.f) & 0xffffu); }
; __device__ __forceinline__ void cvt_tile(unsigned char* lds, const float* src, int ld, int n_begin, int K, bf16_t* dst, int Kd, int koff, int mode, int roff, int t, int tid) {
;     const int ntk = Kd / 64; unsigned short* tile = (unsigned short*)lds;
;     const int tn = t / ntk, tk = t - tn * ntk; const int n0 = tn * 64, k0 = tk * 64;
;     const bool valid = (src != nullptr) && (k0 >= koff) && (k0 < koff + K);
;     __syncthreads();
;     if (valid) {
; #pragma unroll
;         for (int it = 0; it < 2; ++it) { const int idx = tid + 512 * it, kr = idx >> 4, nc4 = idx & 15;
;             const f32x4 v = *(const f32x4*)(src + (size_t)(k0 - koff + kr) * ld + n_begin + n0 + 4 * nc4);
; #pragma unroll
;             for (int j = 0; j < 4; ++j) tile[(4 * nc4 + j) * 66 + kr] = f2bf(v[j]); }
;     }
; __device__ __forceinline__ void cvt_ffn_tile(unsigned char* lds, unsigned char* ws, const float* w_in, const float* w_out, int gt, int tid) {
;     bf16_t* WA = (bf16_t*)(ws + WS_WA); bf16_t* WB = (bf16_t*)(ws + WS_WB);
;     if (gt < 704) cvt_tile(lds, w_in, NFF, 0, DM, WA, DM, 0, 1, 0, gt, tid);
;     else if (gt < 1408) cvt_tile(lds, w_in, NFF, DFF, DM, WA, DM, 0, 1, 128, gt - 704, tid);
;     else cvt_tile(lds, w_out, DM, 0, DFF, WB, DFF, 0, 0, 0, gt - 1408, tid);
.LBB0_184:
	s_andn2_saveexec_b64 s[10:11], s[10:11]
	s_cbranch_execz .LBB0_190
	s_waitcnt lgkmcnt(1)
	v_add_u32_e32 v0, 0xfffffd40, v13
	v_lshrrev_b32_e32 v1, 4, v0
	v_lshlrev_b32_e32 v112, 6, v1
	v_lshlrev_b32_e32 v1, 10, v1
	v_lshlrev_b32_e32 v0, 6, v0
	v_sub_u32_e32 v4, v0, v1
	s_movk_i32 s2, 0x400
	v_cmp_gt_u32_e64 s[6:7], s2, v4
	s_and_b64 s[6:7], s[46:47], s[6:7]
	s_waitcnt lgkmcnt(0)
	s_barrier
	s_and_saveexec_b64 s[16:17], s[6:7]
	s_cbranch_execz .LBB0_187
	v_lshl_add_u64 v[6:7], v[112:113], 2, v[164:165]
	v_add_u32_e32 v0, v4, v171
	s_movk_i32 s12, 0x5800
	v_mad_i64_i32 v[0:1], s[2:3], v0, s12, v[6:7]
	global_load_dwordx4 v[0:3], v[0:1], off
	v_add_u32_e32 v64, v4, v199
	v_mad_i64_i32 v[64:65], s[2:3], v64, s12, v[6:7]
	global_load_dwordx4 v[64:67], v[64:65], off
	v_add_u32_e32 v5, v197, v198
	s_waitcnt vmcnt(1)
	v_cvt_pk_bf16_f32 v0, v0, s0
	ds_write_b16 v5, v0
	v_cvt_pk_bf16_f32 v0, v1, s0
	ds_write_b16 v5, v0 offset:132
	v_cvt_pk_bf16_f32 v0, v2, s0
	ds_write_b16 v5, v0 offset:264
	v_cvt_pk_bf16_f32 v0, v3, s0
	ds_write_b16 v5, v0 offset:396
	v_add_u32_e32 v5, v200, v198
	s_waitcnt vmcnt(0)
	v_cvt_pk_bf16_f32 v0, v64, s0
	ds_write_b16 v5, v0
	v_cvt_pk_bf16_f32 v0, v65, s0
	ds_write_b16 v5, v0 offset:132
	v_cvt_pk_bf16_f32 v0, v66, s0
	ds_write_b16 v5, v0 offset:264
	v_cvt_pk_bf16_f32 v0, v67, s0
	ds_write_b16 v5, v0 offset:396

; __device__ __forceinline__ unsigned short f2bf(float f) { return (unsigned short)(pk2(f, 0.f) & 0xffffu); }
; __device__ __forceinline__ void cvt_tile(unsigned char* lds, const float* src, int ld, int n_begin, int K, bf16_t* dst, int Kd, int koff, int mode, int roff, int t, int tid) {
;     const int ntk = Kd / 64; unsigned short* tile = (unsigned short*)lds;
;     const int tn = t / ntk, tk = t - tn * ntk; const int n0 = tn * 64, k0 = tk * 64;
;     const bool valid = (src != nullptr) && (k0 >= koff) && (k0 < koff + K);
;     __syncthreads();
;     if (valid) {
; #pragma unroll
;         for (int it = 0; it < 2; ++it) { const int idx = tid + 512 * it, kr = idx >> 4, nc4 = idx & 15;
;             const f32x4 v = *(const f32x4*)(src + (size_t)(k0 - koff + kr) * ld + n_begin + n0 + 4 * nc4);
; #pragma unroll
;             for (int j = 0; j < 4; ++j) tile[(4 * nc4 + j) * 66 + kr] = f2bf(v[j]); }
;     }
;     __syncthreads();
;     { const int n = tid >> 3, kc = (tid & 7) * 8; u32x4 w = (u32x4){0u, 0u, 0u, 0u};
;       if (valid) { const unsigned* tp = (const unsigned*)(tile + n * 66 + kc); w.x = tp[0]; w.y = tp[1]; w.z = tp[2]; w.w = tp[3]; }
;       const int nl = n0 + n; const int drow = (mode == 0) ? (nl + roff) : (256 * (nl >> 7) + (nl & 127) + roff);
; __device__ __forceinline__ void cvt_ffn_tile(unsigned char* lds, unsigned char* ws, const float* w_in, const float* w_out, int gt, int tid) {
;     bf16_t* WA = (bf16_t*)(ws + WS_WA); bf16_t* WB = (bf16_t*)(ws + WS_WB);
;     if (gt < 704) cvt_tile(lds, w_in, NFF, 0, DM, WA, DM, 0, 1, 0, gt, tid);
;     else if (gt < 1408) cvt_tile(lds, w_in, NFF, DFF, DM, WA, DM, 0, 1, 128, gt - 704, tid);
;     else cvt_tile(lds, w_out, DM, 0, DFF, WB, DFF, 0, 0, 0, gt - 1408, tid);
.LBB0_191:
	s_or_saveexec_b64 s[0:1], s[0:1]
	v_lshrrev_b32_e32 v5, 1, v12
	v_lshlrev_b32_e32 v112, 6, v5
	v_lshlrev_b32_e32 v14, 10, v5
	v_add_u32_e32 v5, v112, v201
	v_lshlrev_b32_e32 v6, 1, v5
	v_and_b32_e32 v5, 0x7f, v5
	s_movk_i32 s2, 0xff00
	v_and_or_b32 v6, v6, s2, v5
	v_ashrrev_i32_e32 v7, 31, v6
	v_lshlrev_b64 v[6:7], 11, v[6:7]
	v_lshl_add_u64 v[6:7], s[26:27], 0, v[6:7]
	s_xor_b64 exec, exec, s[0:1]
	s_cbranch_execz .LBB0_197
	s_waitcnt lgkmcnt(1)
	v_lshlrev_b32_e32 v0, 9, v12
	v_sub_u32_e32 v4, v0, v14
	s_movk_i32 s2, 0x400
	v_cmp_gt_u32_e64 s[6:7], s2, v4
	s_and_b64 s[6:7], s[46:47], s[6:7]
	s_waitcnt lgkmcnt(0)
	s_barrier
	s_and_saveexec_b64 s[10:11], s[6:7]
	s_cbranch_execz .LBB0_194
	v_lshl_add_u64 v[8:9], v[112:113], 2, v[162:163]
	v_add_u32_e32 v0, v4, v171
	s_movk_i32 s12, 0x5800
	v_mad_i64_i32 v[0:1], s[2:3], v0, s12, v[8:9]
	global_load_dwordx4 v[0:3], v[0:1], off
	v_add_u32_e32 v64, v4, v199
	v_mad_i64_i32 v[64:65], s[2:3], v64, s12, v[8:9]
	global_load_dwordx4 v[64:67], v[64:65], off
	v_add_u32_e32 v5, v197, v198
	s_waitcnt vmcnt(1)
	v_cvt_pk_bf16_f32 v0, v0, s0
	ds_write_b16 v5, v0
	v_cvt_pk_bf16_f32 v0, v1, s0
	ds_write_b16 v5, v0 offset:132
	v_cvt_pk_bf16_f32 v0, v2, s0
	ds_write_b16 v5, v0 offset:264
	v_cvt_pk_bf16_f32 v0, v3, s0
	ds_write_b16 v5, v0 offset:396
	v_add_u32_e32 v5, v200, v198
	s_waitcnt vmcnt(0)
	v_cvt_pk_bf16_f32 v0, v64, s0
	ds_write_b16 v5, v0
	v_cvt_pk_bf16_f32 v0, v65, s0
	ds_write_b16 v5, v0 offset:132
	v_cvt_pk_bf16_f32 v0, v66, s0
	ds_write_b16 v5, v0 offset:264
	v_cvt_pk_bf16_f32 v0, v67, s0
	ds_write_b16 v5, v0 offset:396

; __device__ __forceinline__ unsigned short f2bf(float f) { return (unsigned short)(pk2(f, 0.f) & 0xffffu); }
; __device__ __forceinline__ void cvt_tile(unsigned char* lds, const float* src, int ld, int n_begin, int K, bf16_t* dst, int Kd, int koff, int mode, int roff, int t, int tid) {
;     const int ntk = Kd / 64; unsigned short* tile = (unsigned short*)lds;
;     const int tn = t / ntk, tk = t - tn * ntk; const int n0 = tn * 64, k0 = tk * 64;
;     const bool valid = (src != nullptr) && (k0 >= koff) && (k0 < koff + K);
;     __syncthreads();
;     if (valid) {
; #pragma unroll
;         for (int it = 0; it < 2; ++it) { const int idx = tid + 512 * it, kr = idx >> 4, nc4 = idx & 15;
;             const f32x4 v = *(const f32x4*)(src + (size_t)(k0 - koff + kr) * ld + n_begin + n0 + 4 * nc4);
; #pragma unroll
;             for (int j = 0; j < 4; ++j) tile[(4 * nc4 + j) * 66 + kr] = f2bf(v[j]); }
;     }
;     __syncthreads();
;     { const int n = tid >> 3, kc = (tid & 7) * 8; u32x4 w = (u32x4){0u, 0u, 0u, 0u};
;       if (valid) { const unsigned* tp = (const unsigned*)(tile + n * 66 + kc); w.x = tp[0]; w.y = tp[1]; w.z = tp[2]; w.w = tp[3]; }
;       const int nl = n0 + n; const int drow = (mode == 0) ? (nl + roff) : (256 * (nl >> 7) + (nl & 127) + roff);
;       *(u32x4*)(dst + (size_t)drow * Kd + k0 + kc) = w; }
; __device__ __forceinline__ void cvt_ffn_tile(unsigned char* lds, unsigned char* ws, const float* w_in, const float* w_out, int gt, int tid) {
;     bf16_t* WA = (bf16_t*)(ws + WS_WA); bf16_t* WB = (bf16_t*)(ws + WS_WB);
;     if (gt < 704) cvt_tile(lds, w_in, NFF, 0, DM, WA, DM, 0, 1, 0, gt, tid);
;     else if (gt < 1408) cvt_tile(lds, w_in, NFF, DFF, DM, WA, DM, 0, 1, 128, gt - 704, tid);
;     else cvt_tile(lds, w_out, DM, 0, DFF, WB, DFF, 0, 0, 0, gt - 1408, tid);
.LBB0_197:
	s_or_b64 exec, exec, s[0:1]
	v_ashrrev_i32_e32 v5, 31, v4
	v_lshl_add_u64 v[8:9], v[4:5], 1, v[8:9]
	v_lshlrev_b32_e32 v4, 1, v158
	v_mov_b32_e32 v5, v113
	v_lshl_add_u64 v[8:9], v[8:9], 0, v[4:5]
	s_waitcnt lgkmcnt(0)
	global_store_dwordx4 v[8:9], v[0:3], off
	s_and_saveexec_b64 s[0:1], vcc
	s_xor_b64 s[0:1], exec, s[0:1]
	s_cbranch_execz .LBB0_211
	s_movk_i32 s2, 0xaf
	v_cmp_lt_u32_e64 s[6:7], s2, v12
	s_and_saveexec_b64 s[2:3], s[6:7]
	s_xor_b64 s[10:11], exec, s[2:3]
	s_cbranch_execz .LBB0_204
	v_add_u32_e32 v0, 0xfffffa81, v13
	v_mul_u32_u24_e32 v1, 0xba2f, v0
	v_lshrrev_b32_e32 v1, 21, v1
	s_movk_i32 s2, 0xffd4
	v_mad_i32_i24 v0, v1, s2, v0
	v_cmp_gt_u32_e64 s[6:7], 44, v0
	v_lshlrev_b32_e32 v5, 6, v1
	v_lshlrev_b32_e32 v8, 6, v0
	s_and_b64 s[6:7], s[28:29], s[6:7]
	s_waitcnt vmcnt(63) expcnt(7) lgkmcnt(15)
	s_barrier
	s_and_saveexec_b64 s[16:17], s[6:7]
	s_cbranch_execz .LBB0_201
	v_lshlrev_b32_e32 v0, 2, v5
	v_mov_b32_e32 v1, v113
	v_lshl_add_u64 v[10:11], v[160:161], 0, v[0:1]
	v_add_u32_e32 v0, v8, v171
	v_ashrrev_i32_e32 v1, 31, v0
	v_lshlrev_b64 v[0:1], 12, v[0:1]
	v_lshl_add_u64 v[0:1], v[10:11], 0, v[0:1]
	global_load_dwordx4 v[0:3], v[0:1], off
	v_add_u32_e32 v64, v8, v199
	v_ashrrev_i32_e32 v65, 31, v64
	v_lshlrev_b64 v[64:65], 12, v[64:65]
	v_lshl_add_u64 v[64:65], v[10:11], 0, v[64:65]
	global_load_dwordx4 v[64:67], v[64:65], off
	v_add_u32_e32 v9, v197, v198
	s_waitcnt vmcnt(1)
	v_cvt_pk_bf16_f32 v0, v0, s0
	ds_write_b16 v9, v0
	v_cvt_pk_bf16_f32 v0, v1, s0
	ds_write_b16 v9, v0 offset:132
	v_cvt_pk_bf16_f32 v0, v2, s0
	ds_write_b16 v9, v0 offset:264
	v_cvt_pk_bf16_f32 v0, v3, s0
	ds_write_b16 v9, v0 offset:396
	v_add_u32_e32 v9, v200, v198
	s_waitcnt vmcnt(0)
	v_cvt_pk_bf16_f32 v0, v64, s0
	ds_write_b16 v9, v0
	v_cvt_pk_bf16_f32 v0, v65, s0
	ds_write_b16 v9, v0 offset:132
	v_cvt_pk_bf16_f32 v0, v66, s0
	ds_write_b16 v9, v0 offset:264
	v_cvt_pk_bf16_f32 v0, v67, s0
	ds_write_b16 v9, v0 offset:396

; __device__ __forceinline__ unsigned short f2bf(float f) { return (unsigned short)(pk2(f, 0.f) & 0xffffu); }
; __device__ __forceinline__ void cvt_tile(unsigned char* lds, const float* src, int ld, int n_begin, int K, bf16_t* dst, int Kd, int koff, int mode, int roff, int t, int tid) {
;     const int ntk = Kd / 64; unsigned short* tile = (unsigned short*)lds;
;     const int tn = t / ntk, tk = t - tn * ntk; const int n0 = tn * 64, k0 = tk * 64;
;     const bool valid = (src != nullptr) && (k0 >= koff) && (k0 < koff + K);
;     __syncthreads();
;     if (valid) {
; #pragma unroll
;         for (int it = 0; it < 2; ++it) { const int idx = tid + 512 * it, kr = idx >> 4, nc4 = idx & 15;
;             const f32x4 v = *(const f32x4*)(src + (size_t)(k0 - koff + kr) * ld + n_begin + n0 + 4 * nc4);
; #pragma unroll
;             for (int j = 0; j < 4; ++j) tile[(4 * nc4 + j) * 66 + kr] = f2bf(v[j]); }
;     }
; __device__ __forceinline__ void cvt_ffn_tile(unsigned char* lds, unsigned char* ws, const float* w_in, const float* w_out, int gt, int tid) {
;     bf16_t* WA = (bf16_t*)(ws + WS_WA); bf16_t* WB = (bf16_t*)(ws + WS_WB);
;     if (gt < 704) cvt_tile(lds, w_in, NFF, 0, DM, WA, DM, 0, 1, 0, gt, tid);
;     else if (gt < 1408) cvt_tile(lds, w_in, NFF, DFF, DM, WA, DM, 0, 1, 128, gt - 704, tid);
;     else cvt_tile(lds, w_out, DM, 0, DFF, WB, DFF, 0, 0, 0, gt - 1408, tid);
.LBB0_204:
	s_andn2_saveexec_b64 s[10:11], s[10:11]
	s_cbranch_execz .LBB0_210
	s_waitcnt lgkmcnt(1)
	v_add_u32_e32 v0, 0xfffffd41, v13
	v_lshrrev_b32_e32 v1, 4, v0
	v_lshlrev_b32_e32 v10, 6, v1
	v_lshlrev_b32_e32 v1, 10, v1
	v_lshlrev_b32_e32 v0, 6, v0
	v_sub_u32_e32 v8, v0, v1
	s_movk_i32 s2, 0x400
	v_cmp_gt_u32_e64 s[6:7], s2, v8
	s_and_b64 s[6:7], s[46:47], s[6:7]
	s_waitcnt lgkmcnt(0)
	s_barrier
	s_and_saveexec_b64 s[16:17], s[6:7]
	s_cbranch_execz .LBB0_207
	v_mov_b32_e32 v11, v113
	v_lshl_add_u64 v[16:17], v[10:11], 2, v[164:165]
	v_add_u32_e32 v0, v8, v171
	s_movk_i32 s12, 0x5800
	v_mad_i64_i32 v[0:1], s[2:3], v0, s12, v[16:17]
	global_load_dwordx4 v[0:3], v[0:1], off
	v_add_u32_e32 v64, v8, v199
	v_mad_i64_i32 v[64:65], s[2:3], v64, s12, v[16:17]
	global_load_dwordx4 v[64:67], v[64:65], off
	v_add_u32_e32 v5, v197, v198
	s_waitcnt vmcnt(1)
	v_cvt_pk_bf16_f32 v0, v0, s0
	ds_write_b16 v5, v0
	v_cvt_pk_bf16_f32 v0, v1, s0
	ds_write_b16 v5, v0 offset:132
	v_cvt_pk_bf16_f32 v0, v2, s0
	ds_write_b16 v5, v0 offset:264
	v_cvt_pk_bf16_f32 v0, v3, s0
	ds_write_b16 v5, v0 offset:396
	v_add_u32_e32 v5, v200, v198
	s_waitcnt vmcnt(0)
	v_cvt_pk_bf16_f32 v0, v64, s0
	ds_write_b16 v5, v0
	v_cvt_pk_bf16_f32 v0, v65, s0
	ds_write_b16 v5, v0 offset:132
	v_cvt_pk_bf16_f32 v0, v66, s0
	ds_write_b16 v5, v0 offset:264
	v_cvt_pk_bf16_f32 v0, v67, s0
	ds_write_b16 v5, v0 offset:396

; __device__ __forceinline__ unsigned short f2bf(float f) { return (unsigned short)(pk2(f, 0.f) & 0xffffu); }
; __device__ __forceinline__ void cvt_tile(unsigned char* lds, const float* src, int ld, int n_begin, int K, bf16_t* dst, int Kd, int koff, int mode, int roff, int t, int tid) {
;     const int ntk = Kd / 64; unsigned short* tile = (unsigned short*)lds;
;     const int tn = t / ntk, tk = t - tn * ntk; const int n0 = tn * 64, k0 = tk * 64;
;     const bool valid = (src != nullptr) && (k0 >= koff) && (k0 < koff + K);
;     __syncthreads();
;     if (valid) {
; #pragma unroll
;         for (int it = 0; it < 2; ++it) { const int idx = tid + 512 * it, kr = idx >> 4, nc4 = idx & 15;
;             const f32x4 v = *(const f32x4*)(src + (size_t)(k0 - koff + kr) * ld + n_begin + n0 + 4 * nc4);
; #pragma unroll
;             for (int j = 0; j < 4; ++j) tile[(4 * nc4 + j) * 66 + kr] = f2bf(v[j]); }
;     }
; __device__ __forceinline__ void cvt_ffn_tile(unsigned char* lds, unsigned char* ws, const float* w_in, const float* w_out, int gt, int tid) {
;     bf16_t* WA = (bf16_t*)(ws + WS_WA); bf16_t* WB = (bf16_t*)(ws + WS_WB);
;     if (gt < 704) cvt_tile(lds, w_in, NFF, 0, DM, WA, DM, 0, 1, 0, gt, tid);
;     else if (gt < 1408) cvt_tile(lds, w_in, NFF, DFF, DM, WA, DM, 0, 1, 128, gt - 704, tid);
;     else cvt_tile(lds, w_out, DM, 0, DFF, WB, DFF, 0, 0, 0, gt - 1408, tid);
.LBB0_211:
	s_andn2_saveexec_b64 s[0:1], s[0:1]
	s_cbranch_execz .LBB0_217
	s_waitcnt lgkmcnt(1)
	v_lshl_or_b32 v0, v12, 9, 64
	v_sub_u32_e32 v8, v0, v14
	s_movk_i32 s2, 0x400
	v_cmp_gt_u32_e64 s[6:7], s2, v8
	s_and_b64 s[6:7], s[46:47], s[6:7]
	s_waitcnt lgkmcnt(0)
	s_barrier
	s_and_saveexec_b64 s[10:11], s[6:7]
	s_cbranch_execz .LBB0_214
	v_lshl_add_u64 v[10:11], v[112:113], 2, v[162:163]
	v_add_u32_e32 v0, v8, v171
	s_movk_i32 s12, 0x5800
	v_mad_i64_i32 v[0:1], s[2:3], v0, s12, v[10:11]
	global_load_dwordx4 v[0:3], v[0:1], off
	v_add_u32_e32 v64, v8, v199
	v_mad_i64_i32 v[64:65], s[2:3], v64, s12, v[10:11]
	global_load_dwordx4 v[64:67], v[64:65], off
	v_add_u32_e32 v5, v197, v198
	s_waitcnt vmcnt(1)
	v_cvt_pk_bf16_f32 v0, v0, s0
	ds_write_b16 v5, v0
	v_cvt_pk_bf16_f32 v0, v1, s0
	ds_write_b16 v5, v0 offset:132
	v_cvt_pk_bf16_f32 v0, v2, s0
	ds_write_b16 v5, v0 offset:264
	v_cvt_pk_bf16_f32 v0, v3, s0
	ds_write_b16 v5, v0 offset:396
	v_add_u32_e32 v5, v200, v198
	s_waitcnt vmcnt(0)
	v_cvt_pk_bf16_f32 v0, v64, s0
	ds_write_b16 v5, v0
	v_cvt_pk_bf16_f32 v0, v65, s0
	ds_write_b16 v5, v0 offset:132
	v_cvt_pk_bf16_f32 v0, v66, s0
	ds_write_b16 v5, v0 offset:264
	v_cvt_pk_bf16_f32 v0, v67, s0
	ds_write_b16 v5, v0 offset:396

; __device__ __forceinline__ unsigned short f2bf(float f) { return (unsigned short)(pk2(f, 0.f) & 0xffffu); }
; __device__ __forceinline__ void cvt_tile(unsigned char* lds, const float* src, int ld, int n_begin, int K, bf16_t* dst, int Kd, int koff, int mode, int roff, int t, int tid) {
;     const int ntk = Kd / 64; unsigned short* tile = (unsigned short*)lds;
;     const int tn = t / ntk, tk = t - tn * ntk; const int n0 = tn * 64, k0 = tk * 64;
;     const bool valid = (src != nullptr) && (k0 >= koff) && (k0 < koff + K);
;     __syncthreads();
;     if (valid) {
; #pragma unroll
;         for (int it = 0; it < 2; ++it) { const int idx = tid + 512 * it, kr = idx >> 4, nc4 = idx & 15;
;             const f32x4 v = *(const f32x4*)(src + (size_t)(k0 - koff + kr) * ld + n_begin + n0 + 4 * nc4);
; #pragma unroll
;             for (int j = 0; j < 4; ++j) tile[(4 * nc4 + j) * 66 + kr] = f2bf(v[j]); }
;     }
;     __syncthreads();
;     { const int n = tid >> 3, kc = (tid & 7) * 8; u32x4 w = (u32x4){0u, 0u, 0u, 0u};
;       if (valid) { const unsigned* tp = (const unsigned*)(tile + n * 66 + kc); w.x = tp[0]; w.y = tp[1]; w.z = tp[2]; w.w = tp[3]; }
;       const int nl = n0 + n; const int drow = (mode == 0) ? (nl + roff) : (256 * (nl >> 7) + (nl & 127) + roff);
;       *(u32x4*)(dst + (size_t)drow * Kd + k0 + kc) = w; }
; __device__ __forceinline__ void cvt_ffn_tile(unsigned char* lds, unsigned char* ws, const float* w_in, const float* w_out, int gt, int tid) {
;     bf16_t* WA = (bf16_t*)(ws + WS_WA); bf16_t* WB = (bf16_t*)(ws + WS_WB);
;     if (gt < 704) cvt_tile(lds, w_in, NFF, 0, DM, WA, DM, 0, 1, 0, gt, tid);
;     else if (gt < 1408) cvt_tile(lds, w_in, NFF, DFF, DM, WA, DM, 0, 1, 128, gt - 704, tid);
;     else cvt_tile(lds, w_out, DM, 0, DFF, WB, DFF, 0, 0, 0, gt - 1408, tid);
.LBB0_217:
	s_or_b64 exec, exec, s[0:1]
	v_ashrrev_i32_e32 v9, 31, v8
	v_lshl_add_u64 v[8:9], v[8:9], 1, v[10:11]
	v_mov_b32_e32 v5, v113
	v_lshl_add_u64 v[8:9], v[8:9], 0, v[4:5]
	s_waitcnt lgkmcnt(0)
	global_store_dwordx4 v[8:9], v[0:3], off
	s_and_saveexec_b64 s[0:1], vcc
	s_xor_b64 s[0:1], exec, s[0:1]
	s_cbranch_execz .LBB0_231
	s_movk_i32 s2, 0xaf
	v_cmp_lt_u32_e64 s[6:7], s2, v12
	s_and_saveexec_b64 s[2:3], s[6:7]
	s_xor_b64 s[10:11], exec, s[2:3]
	s_cbranch_execz .LBB0_224
	v_add_u32_e32 v0, 0xfffffa82, v13
	v_mul_u32_u24_e32 v1, 0xba2f, v0
	v_lshrrev_b32_e32 v1, 21, v1
	s_movk_i32 s2, 0xffd4
	v_mad_i32_i24 v0, v1, s2, v0
	v_cmp_gt_u32_e64 s[6:7], 44, v0
	v_lshlrev_b32_e32 v5, 6, v1
	v_lshlrev_b32_e32 v8, 6, v0
	s_and_b64 s[6:7], s[28:29], s[6:7]
	s_waitcnt vmcnt(63) expcnt(7) lgkmcnt(15)
	s_barrier
	s_and_saveexec_b64 s[16:17], s[6:7]
	s_cbranch_execz .LBB0_221
	v_lshlrev_b32_e32 v0, 2, v5
	v_mov_b32_e32 v1, v113
	v_lshl_add_u64 v[10:11], v[160:161], 0, v[0:1]
	v_add_u32_e32 v0, v8, v171
	v_ashrrev_i32_e32 v1, 31, v0
	v_lshlrev_b64 v[0:1], 12, v[0:1]
	v_lshl_add_u64 v[0:1], v[10:11], 0, v[0:1]
	global_load_dwordx4 v[0:3], v[0:1], off
	v_add_u32_e32 v64, v8, v199
	v_ashrrev_i32_e32 v65, 31, v64
	v_lshlrev_b64 v[64:65], 12, v[64:65]
	v_lshl_add_u64 v[64:65], v[10:11], 0, v[64:65]
	global_load_dwordx4 v[64:67], v[64:65], off
	v_add_u32_e32 v9, v197, v198
	s_waitcnt vmcnt(1)
	v_cvt_pk_bf16_f32 v0, v0, s0
	ds_write_b16 v9, v0
	v_cvt_pk_bf16_f32 v0, v1, s0
	ds_write_b16 v9, v0 offset:132
	v_cvt_pk_bf16_f32 v0, v2, s0
	ds_write_b16 v9, v0 offset:264
	v_cvt_pk_bf16_f32 v0, v3, s0
	ds_write_b16 v9, v0 offset:396
	v_add_u32_e32 v9, v200, v198
	s_waitcnt vmcnt(0)
	v_cvt_pk_bf16_f32 v0, v64, s0
	ds_write_b16 v9, v0
	v_cvt_pk_bf16_f32 v0, v65, s0
	ds_write_b16 v9, v0 offset:132
	v_cvt_pk_bf16_f32 v0, v66, s0
	ds_write_b16 v9, v0 offset:264
	v_cvt_pk_bf16_f32 v0, v67, s0
	ds_write_b16 v9, v0 offset:396

; __device__ __forceinline__ unsigned short f2bf(float f) { return (unsigned short)(pk2(f, 0.f) & 0xffffu); }
; __device__ __forceinline__ void cvt_tile(unsigned char* lds, const float* src, int ld, int n_begin, int K, bf16_t* dst, int Kd, int koff, int mode, int roff, int t, int tid) {
;     const int ntk = Kd / 64; unsigned short* tile = (unsigned short*)lds;
;     const int tn = t / ntk, tk = t - tn * ntk; const int n0 = tn * 64, k0 = tk * 64;
;     const bool valid = (src != nullptr) && (k0 >= koff) && (k0 < koff + K);
;     __syncthreads();
;     if (valid) {
; #pragma unroll
;         for (int it = 0; it < 2; ++it) { const int idx = tid + 512 * it, kr = idx >> 4, nc4 = idx & 15;
;             const f32x4 v = *(const f32x4*)(src + (size_t)(k0 - koff + kr) * ld + n_begin + n0 + 4 * nc4);
; #pragma unroll
;             for (int j = 0; j < 4; ++j) tile[(4 * nc4 + j) * 66 + kr] = f2bf(v[j]); }
;     }
; __device__ __forceinline__ void cvt_ffn_tile(unsigned char* lds, unsigned char* ws, const float* w_in, const float* w_out, int gt, int tid) {
;     bf16_t* WA = (bf16_t*)(ws + WS_WA); bf16_t* WB = (bf16_t*)(ws + WS_WB);
;     if (gt < 704) cvt_tile(lds, w_in, NFF, 0, DM, WA, DM, 0, 1, 0, gt, tid);
;     else if (gt < 1408) cvt_tile(lds, w_in, NFF, DFF, DM, WA, DM, 0, 1, 128, gt - 704, tid);
;     else cvt_tile(lds, w_out, DM, 0, DFF, WB, DFF, 0, 0, 0, gt - 1408, tid);
.LBB0_224:
	s_andn2_saveexec_b64 s[10:11], s[10:11]
	s_cbranch_execz .LBB0_230
	s_waitcnt lgkmcnt(1)
	v_add_u32_e32 v0, 0xfffffd42, v13
	v_lshrrev_b32_e32 v1, 4, v0
	v_lshlrev_b32_e32 v10, 6, v1
	v_lshlrev_b32_e32 v1, 10, v1
	v_lshlrev_b32_e32 v0, 6, v0
	v_sub_u32_e32 v8, v0, v1
	s_movk_i32 s2, 0x400
	v_cmp_gt_u32_e64 s[6:7], s2, v8
	s_and_b64 s[6:7], s[46:47], s[6:7]
	s_waitcnt lgkmcnt(0)
	s_barrier
	s_and_saveexec_b64 s[16:17], s[6:7]
	s_cbranch_execz .LBB0_227
	v_mov_b32_e32 v11, v113
	v_lshl_add_u64 v[16:17], v[10:11], 2, v[164:165]
	v_add_u32_e32 v0, v8, v171
	s_movk_i32 s12, 0x5800
	v_mad_i64_i32 v[0:1], s[2:3], v0, s12, v[16:17]
	global_load_dwordx4 v[0:3], v[0:1], off
	v_add_u32_e32 v64, v8, v199
	v_mad_i64_i32 v[64:65], s[2:3], v64, s12, v[16:17]
	global_load_dwordx4 v[64:67], v[64:65], off
	v_add_u32_e32 v5, v197, v198
	s_waitcnt vmcnt(1)
	v_cvt_pk_bf16_f32 v0, v0, s0
	ds_write_b16 v5, v0
	v_cvt_pk_bf16_f32 v0, v1, s0
	ds_write_b16 v5, v0 offset:132
	v_cvt_pk_bf16_f32 v0, v2, s0
	ds_write_b16 v5, v0 offset:264
	v_cvt_pk_bf16_f32 v0, v3, s0
	ds_write_b16 v5, v0 offset:396
	v_add_u32_e32 v5, v200, v198
	s_waitcnt vmcnt(0)
	v_cvt_pk_bf16_f32 v0, v64, s0
	ds_write_b16 v5, v0
	v_cvt_pk_bf16_f32 v0, v65, s0
	ds_write_b16 v5, v0 offset:132
	v_cvt_pk_bf16_f32 v0, v66, s0
	ds_write_b16 v5, v0 offset:264
	v_cvt_pk_bf16_f32 v0, v67, s0
	ds_write_b16 v5, v0 offset:396

; __device__ __forceinline__ unsigned short f2bf(float f) { return (unsigned short)(pk2(f, 0.f) & 0xffffu); }
; __device__ __forceinline__ void cvt_tile(unsigned char* lds, const float* src, int ld, int n_begin, int K, bf16_t* dst, int Kd, int koff, int mode, int roff, int t, int tid) {
;     const int ntk = Kd / 64; unsigned short* tile = (unsigned short*)lds;
;     const int tn = t / ntk, tk = t - tn * ntk; const int n0 = tn * 64, k0 = tk * 64;
;     const bool valid = (src != nullptr) && (k0 >= koff) && (k0 < koff + K);
;     __syncthreads();
;     if (valid) {
; #pragma unroll
;         for (int it = 0; it < 2; ++it) { const int idx = tid + 512 * it, kr = idx >> 4, nc4 = idx & 15;
;             const f32x4 v = *(const f32x4*)(src + (size_t)(k0 - koff + kr) * ld + n_begin + n0 + 4 * nc4);
; #pragma unroll
;             for (int j = 0; j < 4; ++j) tile[(4 * nc4 + j) * 66 + kr] = f2bf(v[j]); }
;     }
; __device__ __forceinline__ void cvt_ffn_tile(unsigned char* lds, unsigned char* ws, const float* w_in, const float* w_out, int gt, int tid) {
;     bf16_t* WA = (bf16_t*)(ws + WS_WA); bf16_t* WB = (bf16_t*)(ws + WS_WB);
;     if (gt < 704) cvt_tile(lds, w_in, NFF, 0, DM, WA, DM, 0, 1, 0, gt, tid);
;     else if (gt < 1408) cvt_tile(lds, w_in, NFF, DFF, DM, WA, DM, 0, 1, 128, gt - 704, tid);
;     else cvt_tile(lds, w_out, DM, 0, DFF, WB, DFF, 0, 0, 0, gt - 1408, tid);
.LBB0_231:
	s_andn2_saveexec_b64 s[0:1], s[0:1]
	s_cbranch_execz .LBB0_237
	s_waitcnt lgkmcnt(1)
	v_mov_b32_e32 v0, 0x80
	v_lshl_or_b32 v0, v12, 9, v0
	v_sub_u32_e32 v8, v0, v14
	s_movk_i32 s2, 0x400
	v_cmp_gt_u32_e64 s[6:7], s2, v8
	s_and_b64 s[6:7], s[46:47], s[6:7]
	s_waitcnt lgkmcnt(0)
	s_barrier
	s_and_saveexec_b64 s[10:11], s[6:7]
	s_cbranch_execz .LBB0_234
	v_lshl_add_u64 v[10:11], v[112:113], 2, v[162:163]
	v_add_u32_e32 v0, v8, v171
	s_movk_i32 s12, 0x5800
	v_mad_i64_i32 v[0:1], s[2:3], v0, s12, v[10:11]
	global_load_dwordx4 v[0:3], v[0:1], off
	v_add_u32_e32 v64, v8, v199
	v_mad_i64_i32 v[64:65], s[2:3], v64, s12, v[10:11]
	global_load_dwordx4 v[64:67], v[64:65], off
	v_add_u32_e32 v5, v197, v198
	s_waitcnt vmcnt(1)
	v_cvt_pk_bf16_f32 v0, v0, s0
	ds_write_b16 v5, v0
	v_cvt_pk_bf16_f32 v0, v1, s0
	ds_write_b16 v5, v0 offset:132
	v_cvt_pk_bf16_f32 v0, v2, s0
	ds_write_b16 v5, v0 offset:264
	v_cvt_pk_bf16_f32 v0, v3, s0
	ds_write_b16 v5, v0 offset:396
	v_add_u32_e32 v5, v200, v198
	s_waitcnt vmcnt(0)
	v_cvt_pk_bf16_f32 v0, v64, s0
	ds_write_b16 v5, v0
	v_cvt_pk_bf16_f32 v0, v65, s0
	ds_write_b16 v5, v0 offset:132
	v_cvt_pk_bf16_f32 v0, v66, s0
	ds_write_b16 v5, v0 offset:264
	v_cvt_pk_bf16_f32 v0, v67, s0
	ds_write_b16 v5, v0 offset:396

; __device__ __forceinline__ unsigned short f2bf(float f) { return (unsigned short)(pk2(f, 0.f) & 0xffffu); }
; __device__ __forceinline__ void cvt_tile(unsigned char* lds, const float* src, int ld, int n_begin, int K, bf16_t* dst, int Kd, int koff, int mode, int roff, int t, int tid) {
;     const int ntk = Kd / 64; unsigned short* tile = (unsigned short*)lds;
;     const int tn = t / ntk, tk = t - tn * ntk; const int n0 = tn * 64, k0 = tk * 64;
;     const bool valid = (src != nullptr) && (k0 >= koff) && (k0 < koff + K);
;     __syncthreads();
;     if (valid) {
; #pragma unroll
;         for (int it = 0; it < 2; ++it) { const int idx = tid + 512 * it, kr = idx >> 4, nc4 = idx & 15;
;             const f32x4 v = *(const f32x4*)(src + (size_t)(k0 - koff + kr) * ld + n_begin + n0 + 4 * nc4);
; #pragma unroll
;             for (int j = 0; j < 4; ++j) tile[(4 * nc4 + j) * 66 + kr] = f2bf(v[j]); }
;     }
;     __syncthreads();
;     { const int n = tid >> 3, kc = (tid & 7) * 8; u32x4 w = (u32x4){0u, 0u, 0u, 0u};
;       if (valid) { const unsigned* tp = (const unsigned*)(tile + n * 66 + kc); w.x = tp[0]; w.y = tp[1]; w.z = tp[2]; w.w = tp[3]; }
;       const int nl = n0 + n; const int drow = (mode == 0) ? (nl + roff) : (256 * (nl >> 7) + (nl & 127) + roff);
;       *(u32x4*)(dst + (size_t)drow * Kd + k0 + kc) = w; }
; __device__ __forceinline__ void cvt_ffn_tile(unsigned char* lds, unsigned char* ws, const float* w_in, const float* w_out, int gt, int tid) {
;     bf16_t* WA = (bf16_t*)(ws + WS_WA); bf16_t* WB = (bf16_t*)(ws + WS_WB);
;     if (gt < 704) cvt_tile(lds, w_in, NFF, 0, DM, WA, DM, 0, 1, 0, gt, tid);
;     else if (gt < 1408) cvt_tile(lds, w_in, NFF, DFF, DM, WA, DM, 0, 1, 128, gt - 704, tid);
;     else cvt_tile(lds, w_out, DM, 0, DFF, WB, DFF, 0, 0, 0, gt - 1408, tid);
.LBB0_237:
	s_or_b64 exec, exec, s[0:1]
	v_ashrrev_i32_e32 v9, 31, v8
	v_lshl_add_u64 v[8:9], v[8:9], 1, v[10:11]
	v_mov_b32_e32 v5, v113
	v_lshl_add_u64 v[8:9], v[8:9], 0, v[4:5]
	s_waitcnt lgkmcnt(0)
	global_store_dwordx4 v[8:9], v[0:3], off
	s_and_saveexec_b64 s[0:1], vcc
	s_xor_b64 s[0:1], exec, s[0:1]
	s_cbranch_execz .LBB0_251
	s_movk_i32 s2, 0xaf
	v_cmp_lt_u32_e64 s[6:7], s2, v12
	s_and_saveexec_b64 s[2:3], s[6:7]
	s_xor_b64 s[10:11], exec, s[2:3]
	s_cbranch_execz .LBB0_244
	v_add_u32_e32 v0, 0xfffffa83, v13
	v_mul_u32_u24_e32 v1, 0xba2f, v0
	v_lshrrev_b32_e32 v1, 21, v1
	s_movk_i32 s2, 0xffd4
	v_mad_i32_i24 v0, v1, s2, v0
	v_cmp_gt_u32_e64 s[6:7], 44, v0
	v_lshlrev_b32_e32 v5, 6, v1
	v_lshlrev_b32_e32 v8, 6, v0
	s_and_b64 s[6:7], s[28:29], s[6:7]
	s_waitcnt vmcnt(63) expcnt(7) lgkmcnt(15)
	s_barrier
	s_and_saveexec_b64 s[16:17], s[6:7]
	s_cbranch_execz .LBB0_241
	v_lshlrev_b32_e32 v0, 2, v5
	v_mov_b32_e32 v1, v113
	v_lshl_add_u64 v[10:11], v[160:161], 0, v[0:1]
	v_add_u32_e32 v0, v8, v171
	v_ashrrev_i32_e32 v1, 31, v0
	v_lshlrev_b64 v[0:1], 12, v[0:1]
	v_lshl_add_u64 v[0:1], v[10:11], 0, v[0:1]
	global_load_dwordx4 v[0:3], v[0:1], off
	v_add_u32_e32 v64, v8, v199
	v_ashrrev_i32_e32 v65, 31, v64
	v_lshlrev_b64 v[64:65], 12, v[64:65]
	v_lshl_add_u64 v[64:65], v[10:11], 0, v[64:65]
	global_load_dwordx4 v[64:67], v[64:65], off
	v_add_u32_e32 v9, v197, v198
	s_waitcnt vmcnt(1)
	v_cvt_pk_bf16_f32 v0, v0, s0
	ds_write_b16 v9, v0
	v_cvt_pk_bf16_f32 v0, v1, s0
	ds_write_b16 v9, v0 offset:132
	v_cvt_pk_bf16_f32 v0, v2, s0
	ds_write_b16 v9, v0 offset:264
	v_cvt_pk_bf16_f32 v0, v3, s0
	ds_write_b16 v9, v0 offset:396
	v_add_u32_e32 v9, v200, v198
	s_waitcnt vmcnt(0)
	v_cvt_pk_bf16_f32 v0, v64, s0
	ds_write_b16 v9, v0
	v_cvt_pk_bf16_f32 v0, v65, s0
	ds_write_b16 v9, v0 offset:132
	v_cvt_pk_bf16_f32 v0, v66, s0
	ds_write_b16 v9, v0 offset:264
	v_cvt_pk_bf16_f32 v0, v67, s0
	ds_write_b16 v9, v0 offset:396

; __device__ __forceinline__ unsigned short f2bf(float f) { return (unsigned short)(pk2(f, 0.f) & 0xffffu); }
; __device__ __forceinline__ void cvt_tile(unsigned char* lds, const float* src, int ld, int n_begin, int K, bf16_t* dst, int Kd, int koff, int mode, int roff, int t, int tid) {
;     const int ntk = Kd / 64; unsigned short* tile = (unsigned short*)lds;
;     const int tn = t / ntk, tk = t - tn * ntk; const int n0 = tn * 64, k0 = tk * 64;
;     const bool valid = (src != nullptr) && (k0 >= koff) && (k0 < koff + K);
;     __syncthreads();
;     if (valid) {
; #pragma unroll
;         for (int it = 0; it < 2; ++it) { const int idx = tid + 512 * it, kr = idx >> 4, nc4 = idx & 15;
;             const f32x4 v = *(const f32x4*)(src + (size_t)(k0 - koff + kr) * ld + n_begin + n0 + 4 * nc4);
; #pragma unroll
;             for (int j = 0; j < 4; ++j) tile[(4 * nc4 + j) * 66 + kr] = f2bf(v[j]); }
;     }
; __device__ __forceinline__ void cvt_ffn_tile(unsigned char* lds, unsigned char* ws, const float* w_in, const float* w_out, int gt, int tid) {
;     bf16_t* WA = (bf16_t*)(ws + WS_WA); bf16_t* WB = (bf16_t*)(ws + WS_WB);
;     if (gt < 704) cvt_tile(lds, w_in, NFF, 0, DM, WA, DM, 0, 1, 0, gt, tid);
;     else if (gt < 1408) cvt_tile(lds, w_in, NFF, DFF, DM, WA, DM, 0, 1, 128, gt - 704, tid);
;     else cvt_tile(lds, w_out, DM, 0, DFF, WB, DFF, 0, 0, 0, gt - 1408, tid);
.LBB0_244:
	s_andn2_saveexec_b64 s[10:11], s[10:11]
	s_cbranch_execz .LBB0_250
	s_waitcnt lgkmcnt(1)
	v_add_u32_e32 v0, 0xfffffd43, v13
	v_lshrrev_b32_e32 v1, 4, v0
	v_lshlrev_b32_e32 v10, 6, v1
	v_lshlrev_b32_e32 v1, 10, v1
	v_lshlrev_b32_e32 v0, 6, v0
	v_sub_u32_e32 v8, v0, v1
	s_movk_i32 s2, 0x400
	v_cmp_gt_u32_e64 s[6:7], s2, v8
	s_and_b64 s[6:7], s[46:47], s[6:7]
	s_waitcnt lgkmcnt(0)
	s_barrier
	s_and_saveexec_b64 s[16:17], s[6:7]
	s_cbranch_execz .LBB0_247
	v_mov_b32_e32 v11, v113
	v_lshl_add_u64 v[16:17], v[10:11], 2, v[164:165]
	v_add_u32_e32 v0, v8, v171
	s_movk_i32 s12, 0x5800
	v_mad_i64_i32 v[0:1], s[2:3], v0, s12, v[16:17]
	global_load_dwordx4 v[0:3], v[0:1], off
	v_add_u32_e32 v64, v8, v199
	v_mad_i64_i32 v[64:65], s[2:3], v64, s12, v[16:17]
	global_load_dwordx4 v[64:67], v[64:65], off
	v_add_u32_e32 v5, v197, v198
	s_waitcnt vmcnt(1)
	v_cvt_pk_bf16_f32 v0, v0, s0
	ds_write_b16 v5, v0
	v_cvt_pk_bf16_f32 v0, v1, s0
	ds_write_b16 v5, v0 offset:132
	v_cvt_pk_bf16_f32 v0, v2, s0
	ds_write_b16 v5, v0 offset:264
	v_cvt_pk_bf16_f32 v0, v3, s0
	ds_write_b16 v5, v0 offset:396
	v_add_u32_e32 v5, v200, v198
	s_waitcnt vmcnt(0)
	v_cvt_pk_bf16_f32 v0, v64, s0
	ds_write_b16 v5, v0
	v_cvt_pk_bf16_f32 v0, v65, s0
	ds_write_b16 v5, v0 offset:132
	v_cvt_pk_bf16_f32 v0, v66, s0
	ds_write_b16 v5, v0 offset:264
	v_cvt_pk_bf16_f32 v0, v67, s0
	ds_write_b16 v5, v0 offset:396

; __device__ __forceinline__ unsigned short f2bf(float f) { return (unsigned short)(pk2(f, 0.f) & 0xffffu); }
; __device__ __forceinline__ void cvt_tile(unsigned char* lds, const float* src, int ld, int n_begin, int K, bf16_t* dst, int Kd, int koff, int mode, int roff, int t, int tid) {
;     const int ntk = Kd / 64; unsigned short* tile = (unsigned short*)lds;
;     const int tn = t / ntk, tk = t - tn * ntk; const int n0 = tn * 64, k0 = tk * 64;
;     const bool valid = (src != nullptr) && (k0 >= koff) && (k0 < koff + K);
;     __syncthreads();
;     if (valid) {
; #pragma unroll
;         for (int it = 0; it < 2; ++it) { const int idx = tid + 512 * it, kr = idx >> 4, nc4 = idx & 15;
;             const f32x4 v = *(const f32x4*)(src + (size_t)(k0 - koff + kr) * ld + n_begin + n0 + 4 * nc4);
; #pragma unroll
;             for (int j = 0; j < 4; ++j) tile[(4 * nc4 + j) * 66 + kr] = f2bf(v[j]); }
;     }
; __device__ __forceinline__ void cvt_ffn_tile(unsigned char* lds, unsigned char* ws, const float* w_in, const float* w_out, int gt, int tid) {
;     bf16_t* WA = (bf16_t*)(ws + WS_WA); bf16_t* WB = (bf16_t*)(ws + WS_WB);
;     if (gt < 704) cvt_tile(lds, w_in, NFF, 0, DM, WA, DM, 0, 1, 0, gt, tid);
;     else if (gt < 1408) cvt_tile(lds, w_in, NFF, DFF, DM, WA, DM, 0, 1, 128, gt - 704, tid);
;     else cvt_tile(lds, w_out, DM, 0, DFF, WB, DFF, 0, 0, 0, gt - 1408, tid);
.LBB0_251:
	s_andn2_saveexec_b64 s[0:1], s[0:1]
	s_cbranch_execz .LBB0_257
	s_waitcnt lgkmcnt(1)
	v_mov_b32_e32 v0, 0xc0
	v_lshl_or_b32 v0, v12, 9, v0
	v_sub_u32_e32 v8, v0, v14
	s_movk_i32 s2, 0x400
	v_cmp_gt_u32_e64 s[6:7], s2, v8
	s_and_b64 s[6:7], s[46:47], s[6:7]
	s_waitcnt lgkmcnt(0)
	s_barrier
	s_and_saveexec_b64 s[10:11], s[6:7]
	s_cbranch_execz .LBB0_254
	v_lshl_add_u64 v[10:11], v[112:113], 2, v[162:163]
	v_add_u32_e32 v0, v8, v171
	s_movk_i32 s12, 0x5800
	v_mad_i64_i32 v[0:1], s[2:3], v0, s12, v[10:11]
	global_load_dwordx4 v[0:3], v[0:1], off
	v_add_u32_e32 v64, v8, v199
	v_mad_i64_i32 v[64:65], s[2:3], v64, s12, v[10:11]
	global_load_dwordx4 v[64:67], v[64:65], off
	v_add_u32_e32 v5, v197, v198
	s_waitcnt vmcnt(1)
	v_cvt_pk_bf16_f32 v0, v0, s0
	ds_write_b16 v5, v0
	v_cvt_pk_bf16_f32 v0, v1, s0
	ds_write_b16 v5, v0 offset:132
	v_cvt_pk_bf16_f32 v0, v2, s0
	ds_write_b16 v5, v0 offset:264
	v_cvt_pk_bf16_f32 v0, v3, s0
	ds_write_b16 v5, v0 offset:396
	v_add_u32_e32 v5, v200, v198
	s_waitcnt vmcnt(0)
	v_cvt_pk_bf16_f32 v0, v64, s0
	ds_write_b16 v5, v0
	v_cvt_pk_bf16_f32 v0, v65, s0
	ds_write_b16 v5, v0 offset:132
	v_cvt_pk_bf16_f32 v0, v66, s0
	ds_write_b16 v5, v0 offset:264
	v_cvt_pk_bf16_f32 v0, v67, s0
	ds_write_b16 v5, v0 offset:396

; __device__ __forceinline__ unsigned short f2bf(float f) { return (unsigned short)(pk2(f, 0.f) & 0xffffu); }
; __device__ __forceinline__ void cvt_tile(unsigned char* lds, const float* src, int ld, int n_begin, int K, bf16_t* dst, int Kd, int koff, int mode, int roff, int t, int tid) {
;     const int ntk = Kd / 64; unsigned short* tile = (unsigned short*)lds;
;     const int tn = t / ntk, tk = t - tn * ntk; const int n0 = tn * 64, k0 = tk * 64;
;     const bool valid = (src != nullptr) && (k0 >= koff) && (k0 < koff + K);
;     __syncthreads();
;     if (valid) {
; #pragma unroll
;         for (int it = 0; it < 2; ++it) { const int idx = tid + 512 * it, kr = idx >> 4, nc4 = idx & 15;
;             const f32x4 v = *(const f32x4*)(src + (size_t)(k0 - koff + kr) * ld + n_begin + n0 + 4 * nc4);
; #pragma unroll
;             for (int j = 0; j < 4; ++j) tile[(4 * nc4 + j) * 66 + kr] = f2bf(v[j]); }
;     }
;     __syncthreads();
;     { const int n = tid >> 3, kc = (tid & 7) * 8; u32x4 w = (u32x4){0u, 0u, 0u, 0u};
;       if (valid) { const unsigned* tp = (const unsigned*)(tile + n * 66 + kc); w.x = tp[0]; w.y = tp[1]; w.z = tp[2]; w.w = tp[3]; }
;       const int nl = n0 + n; const int drow = (mode == 0) ? (nl + roff) : (256 * (nl >> 7) + (nl & 127) + roff);
;       *(u32x4*)(dst + (size_t)drow * Kd + k0 + kc) = w; }
; __device__ __forceinline__ void cvt_ffn_tile(unsigned char* lds, unsigned char* ws, const float* w_in, const float* w_out, int gt, int tid) {
;     bf16_t* WA = (bf16_t*)(ws + WS_WA); bf16_t* WB = (bf16_t*)(ws + WS_WB);
;     if (gt < 704) cvt_tile(lds, w_in, NFF, 0, DM, WA, DM, 0, 1, 0, gt, tid);
;     else if (gt < 1408) cvt_tile(lds, w_in, NFF, DFF, DM, WA, DM, 0, 1, 128, gt - 704, tid);
;     else cvt_tile(lds, w_out, DM, 0, DFF, WB, DFF, 0, 0, 0, gt - 1408, tid);
.LBB0_257:
	s_or_b64 exec, exec, s[0:1]
	v_ashrrev_i32_e32 v9, 31, v8
	v_lshl_add_u64 v[8:9], v[8:9], 1, v[10:11]
	v_mov_b32_e32 v5, v113
	v_lshl_add_u64 v[8:9], v[8:9], 0, v[4:5]
	s_waitcnt lgkmcnt(0)
	global_store_dwordx4 v[8:9], v[0:3], off
	s_and_saveexec_b64 s[0:1], vcc
	s_xor_b64 s[0:1], exec, s[0:1]
	s_cbranch_execz .LBB0_271
	s_movk_i32 s2, 0xaf
	v_cmp_lt_u32_e64 s[6:7], s2, v12
	s_and_saveexec_b64 s[2:3], s[6:7]
	s_xor_b64 s[10:11], exec, s[2:3]
	s_cbranch_execz .LBB0_264
	v_add_u32_e32 v0, 0xfffffa84, v13
	v_mul_u32_u24_e32 v1, 0xba2f, v0
	v_lshrrev_b32_e32 v1, 21, v1
	s_movk_i32 s2, 0xffd4
	v_mad_i32_i24 v0, v1, s2, v0
	v_cmp_gt_u32_e64 s[6:7], 44, v0
	v_lshlrev_b32_e32 v5, 6, v1
	v_lshlrev_b32_e32 v8, 6, v0
	s_and_b64 s[6:7], s[28:29], s[6:7]
	s_waitcnt vmcnt(63) expcnt(7) lgkmcnt(15)
	s_barrier
	s_and_saveexec_b64 s[16:17], s[6:7]
	s_cbranch_execz .LBB0_261
	v_lshlrev_b32_e32 v0, 2, v5
	v_mov_b32_e32 v1, v113
	v_lshl_add_u64 v[10:11], v[160:161], 0, v[0:1]
	v_add_u32_e32 v0, v8, v171
	v_ashrrev_i32_e32 v1, 31, v0
	v_lshlrev_b64 v[0:1], 12, v[0:1]
	v_lshl_add_u64 v[0:1], v[10:11], 0, v[0:1]
	global_load_dwordx4 v[0:3], v[0:1], off
	v_add_u32_e32 v64, v8, v199
	v_ashrrev_i32_e32 v65, 31, v64
	v_lshlrev_b64 v[64:65], 12, v[64:65]
	v_lshl_add_u64 v[64:65], v[10:11], 0, v[64:65]
	global_load_dwordx4 v[64:67], v[64:65], off
	v_add_u32_e32 v9, v197, v198
	s_waitcnt vmcnt(1)
	v_cvt_pk_bf16_f32 v0, v0, s0
	ds_write_b16 v9, v0
	v_cvt_pk_bf16_f32 v0, v1, s0
	ds_write_b16 v9, v0 offset:132
	v_cvt_pk_bf16_f32 v0, v2, s0
	ds_write_b16 v9, v0 offset:264
	v_cvt_pk_bf16_f32 v0, v3, s0
	ds_write_b16 v9, v0 offset:396
	v_add_u32_e32 v9, v200, v198
	s_waitcnt vmcnt(0)
	v_cvt_pk_bf16_f32 v0, v64, s0
	ds_write_b16 v9, v0
	v_cvt_pk_bf16_f32 v0, v65, s0
	ds_write_b16 v9, v0 offset:132
	v_cvt_pk_bf16_f32 v0, v66, s0
	ds_write_b16 v9, v0 offset:264
	v_cvt_pk_bf16_f32 v0, v67, s0
	ds_write_b16 v9, v0 offset:396

; __device__ __forceinline__ unsigned short f2bf(float f) { return (unsigned short)(pk2(f, 0.f) & 0xffffu); }
; __device__ __forceinline__ void cvt_tile(unsigned char* lds, const float* src, int ld, int n_begin, int K, bf16_t* dst, int Kd, int koff, int mode, int roff, int t, int tid) {
;     const int ntk = Kd / 64; unsigned short* tile = (unsigned short*)lds;
;     const int tn = t / ntk, tk = t - tn * ntk; const int n0 = tn * 64, k0 = tk * 64;
;     const bool valid = (src != nullptr) && (k0 >= koff) && (k0 < koff + K);
;     __syncthreads();
;     if (valid) {
; #pragma unroll
;         for (int it = 0; it < 2; ++it) { const int idx = tid + 512 * it, kr = idx >> 4, nc4 = idx & 15;
;             const f32x4 v = *(const f32x4*)(src + (size_t)(k0 - koff + kr) * ld + n_begin + n0 + 4 * nc4);
; #pragma unroll
;             for (int j = 0; j < 4; ++j) tile[(4 * nc4 + j) * 66 + kr] = f2bf(v[j]); }
;     }
; __device__ __forceinline__ void cvt_ffn_tile(unsigned char* lds, unsigned char* ws, const float* w_in, const float* w_out, int gt, int tid) {
;     bf16_t* WA = (bf16_t*)(ws + WS_WA); bf16_t* WB = (bf16_t*)(ws + WS_WB);
;     if (gt < 704) cvt_tile(lds, w_in, NFF, 0, DM, WA, DM, 0, 1, 0, gt, tid);
;     else if (gt < 1408) cvt_tile(lds, w_in, NFF, DFF, DM, WA, DM, 0, 1, 128, gt - 704, tid);
;     else cvt_tile(lds, w_out, DM, 0, DFF, WB, DFF, 0, 0, 0, gt - 1408, tid);
.LBB0_264:
	s_andn2_saveexec_b64 s[10:11], s[10:11]
	s_cbranch_execz .LBB0_270
	s_waitcnt lgkmcnt(1)
	v_add_u32_e32 v0, 0xfffffd44, v13
	v_lshrrev_b32_e32 v1, 4, v0
	v_lshlrev_b32_e32 v10, 6, v1
	v_lshlrev_b32_e32 v1, 10, v1
	v_lshlrev_b32_e32 v0, 6, v0
	v_sub_u32_e32 v8, v0, v1
	s_movk_i32 s2, 0x400
	v_cmp_gt_u32_e64 s[6:7], s2, v8
	s_and_b64 s[6:7], s[46:47], s[6:7]
	s_waitcnt lgkmcnt(0)
	s_barrier
	s_and_saveexec_b64 s[16:17], s[6:7]
	s_cbranch_execz .LBB0_267
	v_mov_b32_e32 v11, v113
	v_lshl_add_u64 v[16:17], v[10:11], 2, v[164:165]
	v_add_u32_e32 v0, v8, v171
	s_movk_i32 s12, 0x5800
	v_mad_i64_i32 v[0:1], s[2:3], v0, s12, v[16:17]
	global_load_dwordx4 v[0:3], v[0:1], off
	v_add_u32_e32 v64, v8, v199
	v_mad_i64_i32 v[64:65], s[2:3], v64, s12, v[16:17]
	global_load_dwordx4 v[64:67], v[64:65], off
	v_add_u32_e32 v5, v197, v198
	s_waitcnt vmcnt(1)
	v_cvt_pk_bf16_f32 v0, v0, s0
	ds_write_b16 v5, v0
	v_cvt_pk_bf16_f32 v0, v1, s0
	ds_write_b16 v5, v0 offset:132
	v_cvt_pk_bf16_f32 v0, v2, s0
	ds_write_b16 v5, v0 offset:264
	v_cvt_pk_bf16_f32 v0, v3, s0
	ds_write_b16 v5, v0 offset:396
	v_add_u32_e32 v5, v200, v198
	s_waitcnt vmcnt(0)
	v_cvt_pk_bf16_f32 v0, v64, s0
	ds_write_b16 v5, v0
	v_cvt_pk_bf16_f32 v0, v65, s0
	ds_write_b16 v5, v0 offset:132
	v_cvt_pk_bf16_f32 v0, v66, s0
	ds_write_b16 v5, v0 offset:264
	v_cvt_pk_bf16_f32 v0, v67, s0
	ds_write_b16 v5, v0 offset:396

; __device__ __forceinline__ unsigned short f2bf(float f) { return (unsigned short)(pk2(f, 0.f) & 0xffffu); }
; __device__ __forceinline__ void cvt_tile(unsigned char* lds, const float* src, int ld, int n_begin, int K, bf16_t* dst, int Kd, int koff, int mode, int roff, int t, int tid) {
;     const int ntk = Kd / 64; unsigned short* tile = (unsigned short*)lds;
;     const int tn = t / ntk, tk = t - tn * ntk; const int n0 = tn * 64, k0 = tk * 64;
;     const bool valid = (src != nullptr) && (k0 >= koff) && (k0 < koff + K);
;     __syncthreads();
;     if (valid) {
; #pragma unroll
;         for (int it = 0; it < 2; ++it) { const int idx = tid + 512 * it, kr = idx >> 4, nc4 = idx & 15;
;             const f32x4 v = *(const f32x4*)(src + (size_t)(k0 - koff + kr) * ld + n_begin + n0 + 4 * nc4);
; #pragma unroll
;             for (int j = 0; j < 4; ++j) tile[(4 * nc4 + j) * 66 + kr] = f2bf(v[j]); }
;     }
; __device__ __forceinline__ void cvt_ffn_tile(unsigned char* lds, unsigned char* ws, const float* w_in, const float* w_out, int gt, int tid) {
;     bf16_t* WA = (bf16_t*)(ws + WS_WA); bf16_t* WB = (bf16_t*)(ws + WS_WB);
;     if (gt < 704) cvt_tile(lds, w_in, NFF, 0, DM, WA, DM, 0, 1, 0, gt, tid);
;     else if (gt < 1408) cvt_tile(lds, w_in, NFF, DFF, DM, WA, DM, 0, 1, 128, gt - 704, tid);
;     else cvt_tile(lds, w_out, DM, 0, DFF, WB, DFF, 0, 0, 0, gt - 1408, tid);
.LBB0_271:
	s_andn2_saveexec_b64 s[0:1], s[0:1]
	s_cbranch_execz .LBB0_277
	s_waitcnt lgkmcnt(1)
	v_lshl_or_b32 v0, v12, 9, v193
	v_sub_u32_e32 v8, v0, v14
	s_movk_i32 s2, 0x400
	v_cmp_gt_u32_e64 s[6:7], s2, v8
	s_and_b64 s[6:7], s[46:47], s[6:7]
	s_waitcnt lgkmcnt(0)
	s_barrier
	s_and_saveexec_b64 s[10:11], s[6:7]
	s_cbranch_execz .LBB0_274
	v_lshl_add_u64 v[10:11], v[112:113], 2, v[162:163]
	v_add_u32_e32 v0, v8, v171
	s_movk_i32 s12, 0x5800
	v_mad_i64_i32 v[0:1], s[2:3], v0, s12, v[10:11]
	global_load_dwordx4 v[0:3], v[0:1], off
	v_add_u32_e32 v64, v8, v199
	v_mad_i64_i32 v[64:65], s[2:3], v64, s12, v[10:11]
	global_load_dwordx4 v[64:67], v[64:65], off
	v_add_u32_e32 v5, v197, v198
	s_waitcnt vmcnt(1)
	v_cvt_pk_bf16_f32 v0, v0, s0
	ds_write_b16 v5, v0
	v_cvt_pk_bf16_f32 v0, v1, s0
	ds_write_b16 v5, v0 offset:132
	v_cvt_pk_bf16_f32 v0, v2, s0
	ds_write_b16 v5, v0 offset:264
	v_cvt_pk_bf16_f32 v0, v3, s0
	ds_write_b16 v5, v0 offset:396
	v_add_u32_e32 v5, v200, v198
	s_waitcnt vmcnt(0)
	v_cvt_pk_bf16_f32 v0, v64, s0
	ds_write_b16 v5, v0
	v_cvt_pk_bf16_f32 v0, v65, s0
	ds_write_b16 v5, v0 offset:132
	v_cvt_pk_bf16_f32 v0, v66, s0
	ds_write_b16 v5, v0 offset:264
	v_cvt_pk_bf16_f32 v0, v67, s0
	ds_write_b16 v5, v0 offset:396

; __device__ __forceinline__ unsigned short f2bf(float f) { return (unsigned short)(pk2(f, 0.f) & 0xffffu); }
; __device__ __forceinline__ void cvt_tile(unsigned char* lds, const float* src, int ld, int n_begin, int K, bf16_t* dst, int Kd, int koff, int mode, int roff, int t, int tid) {
;     const int ntk = Kd / 64; unsigned short* tile = (unsigned short*)lds;
;     const int tn = t / ntk, tk = t - tn * ntk; const int n0 = tn * 64, k0 = tk * 64;
;     const bool valid = (src != nullptr) && (k0 >= koff) && (k0 < koff + K);
;     __syncthreads();
;     if (valid) {
; #pragma unroll
;         for (int it = 0; it < 2; ++it) { const int idx = tid + 512 * it, kr = idx >> 4, nc4 = idx & 15;
;             const f32x4 v = *(const f32x4*)(src + (size_t)(k0 - koff + kr) * ld + n_begin + n0 + 4 * nc4);
; #pragma unroll
;             for (int j = 0; j < 4; ++j) tile[(4 * nc4 + j) * 66 + kr] = f2bf(v[j]); }
;     }
;     __syncthreads();
;     { const int n = tid >> 3, kc = (tid & 7) * 8; u32x4 w = (u32x4){0u, 0u, 0u, 0u};
;       if (valid) { const unsigned* tp = (const unsigned*)(tile + n * 66 + kc); w.x = tp[0]; w.y = tp[1]; w.z = tp[2]; w.w = tp[3]; }
;       const int nl = n0 + n; const int drow = (mode == 0) ? (nl + roff) : (256 * (nl >> 7) + (nl & 127) + roff);
;       *(u32x4*)(dst + (size_t)drow * Kd + k0 + kc) = w; }
; __device__ __forceinline__ void cvt_ffn_tile(unsigned char* lds, unsigned char* ws, const float* w_in, const float* w_out, int gt, int tid) {
;     bf16_t* WA = (bf16_t*)(ws + WS_WA); bf16_t* WB = (bf16_t*)(ws + WS_WB);
;     if (gt < 704) cvt_tile(lds, w_in, NFF, 0, DM, WA, DM, 0, 1, 0, gt, tid);
;     else if (gt < 1408) cvt_tile(lds, w_in, NFF, DFF, DM, WA, DM, 0, 1, 128, gt - 704, tid);
;     else cvt_tile(lds, w_out, DM, 0, DFF, WB, DFF, 0, 0, 0, gt - 1408, tid);
.LBB0_277:
	s_or_b64 exec, exec, s[0:1]
	v_ashrrev_i32_e32 v9, 31, v8
	v_lshl_add_u64 v[8:9], v[8:9], 1, v[10:11]
	v_mov_b32_e32 v5, v113
	v_lshl_add_u64 v[8:9], v[8:9], 0, v[4:5]
	s_waitcnt lgkmcnt(0)
	global_store_dwordx4 v[8:9], v[0:3], off
	s_and_saveexec_b64 s[0:1], vcc
	s_xor_b64 s[0:1], exec, s[0:1]
	s_cbranch_execz .LBB0_291
	s_movk_i32 s2, 0xaf
	v_cmp_lt_u32_e64 s[6:7], s2, v12
	s_and_saveexec_b64 s[2:3], s[6:7]
	s_xor_b64 s[10:11], exec, s[2:3]
	s_cbranch_execz .LBB0_284
	v_add_u32_e32 v0, 0xfffffa85, v13
	v_mul_u32_u24_e32 v1, 0xba2f, v0
	v_lshrrev_b32_e32 v1, 21, v1
	s_movk_i32 s2, 0xffd4
	v_mad_i32_i24 v0, v1, s2, v0
	v_cmp_gt_u32_e64 s[6:7], 44, v0
	v_lshlrev_b32_e32 v5, 6, v1
	v_lshlrev_b32_e32 v8, 6, v0
	s_and_b64 s[6:7], s[28:29], s[6:7]
	s_waitcnt vmcnt(63) expcnt(7) lgkmcnt(15)
	s_barrier
	s_and_saveexec_b64 s[16:17], s[6:7]
	s_cbranch_execz .LBB0_281
	v_lshlrev_b32_e32 v0, 2, v5
	v_mov_b32_e32 v1, v113
	v_lshl_add_u64 v[10:11], v[160:161], 0, v[0:1]
	v_add_u32_e32 v0, v8, v171
	v_ashrrev_i32_e32 v1, 31, v0
	v_lshlrev_b64 v[0:1], 12, v[0:1]
	v_lshl_add_u64 v[0:1], v[10:11], 0, v[0:1]
	global_load_dwordx4 v[0:3], v[0:1], off
	v_add_u32_e32 v64, v8, v199
	v_ashrrev_i32_e32 v65, 31, v64
	v_lshlrev_b64 v[64:65], 12, v[64:65]
	v_lshl_add_u64 v[64:65], v[10:11], 0, v[64:65]
	global_load_dwordx4 v[64:67], v[64:65], off
	v_add_u32_e32 v9, v197, v198
	s_waitcnt vmcnt(1)
	v_cvt_pk_bf16_f32 v0, v0, s0
	ds_write_b16 v9, v0
	v_cvt_pk_bf16_f32 v0, v1, s0
	ds_write_b16 v9, v0 offset:132
	v_cvt_pk_bf16_f32 v0, v2, s0
	ds_write_b16 v9, v0 offset:264
	v_cvt_pk_bf16_f32 v0, v3, s0
	ds_write_b16 v9, v0 offset:396
	v_add_u32_e32 v9, v200, v198
	s_waitcnt vmcnt(0)
	v_cvt_pk_bf16_f32 v0, v64, s0
	ds_write_b16 v9, v0
	v_cvt_pk_bf16_f32 v0, v65, s0
	ds_write_b16 v9, v0 offset:132
	v_cvt_pk_bf16_f32 v0, v66, s0
	ds_write_b16 v9, v0 offset:264
	v_cvt_pk_bf16_f32 v0, v67, s0
	ds_write_b16 v9, v0 offset:396

; __device__ __forceinline__ unsigned short f2bf(float f) { return (unsigned short)(pk2(f, 0.f) & 0xffffu); }
; __device__ __forceinline__ void cvt_tile(unsigned char* lds, const float* src, int ld, int n_begin, int K, bf16_t* dst, int Kd, int koff, int mode, int roff, int t, int tid) {
;     const int ntk = Kd / 64; unsigned short* tile = (unsigned short*)lds;
;     const int tn = t / ntk, tk = t - tn * ntk; const int n0 = tn * 64, k0 = tk * 64;
;     const bool valid = (src != nullptr) && (k0 >= koff) && (k0 < koff + K);
;     __syncthreads();
;     if (valid) {
; #pragma unroll
;         for (int it = 0; it < 2; ++it) { const int idx = tid + 512 * it, kr = idx >> 4, nc4 = idx & 15;
;             const f32x4 v = *(const f32x4*)(src + (size_t)(k0 - koff + kr) * ld + n_begin + n0 + 4 * nc4);
; #pragma unroll
;             for (int j = 0; j < 4; ++j) tile[(4 * nc4 + j) * 66 + kr] = f2bf(v[j]); }
;     }
; __device__ __forceinline__ void cvt_ffn_tile(unsigned char* lds, unsigned char* ws, const float* w_in, const float* w_out, int gt, int tid) {
;     bf16_t* WA = (bf16_t*)(ws + WS_WA); bf16_t* WB = (bf16_t*)(ws + WS_WB);
;     if (gt < 704) cvt_tile(lds, w_in, NFF, 0, DM, WA, DM, 0, 1, 0, gt, tid);
;     else if (gt < 1408) cvt_tile(lds, w_in, NFF, DFF, DM, WA, DM, 0, 1, 128, gt - 704, tid);
;     else cvt_tile(lds, w_out, DM, 0, DFF, WB, DFF, 0, 0, 0, gt - 1408, tid);
.LBB0_284:
	s_andn2_saveexec_b64 s[10:11], s[10:11]
	s_cbranch_execz .LBB0_290
	s_waitcnt lgkmcnt(1)
	v_add_u32_e32 v0, 0xfffffd45, v13
	v_lshrrev_b32_e32 v1, 4, v0
	v_lshlrev_b32_e32 v10, 6, v1
	v_lshlrev_b32_e32 v1, 10, v1
	v_lshlrev_b32_e32 v0, 6, v0
	v_sub_u32_e32 v8, v0, v1
	s_movk_i32 s2, 0x400
	v_cmp_gt_u32_e64 s[6:7], s2, v8
	s_and_b64 s[6:7], s[46:47], s[6:7]
	s_waitcnt lgkmcnt(0)
	s_barrier
	s_and_saveexec_b64 s[16:17], s[6:7]
	s_cbranch_execz .LBB0_287
	v_mov_b32_e32 v11, v113
	v_lshl_add_u64 v[16:17], v[10:11], 2, v[164:165]
	v_add_u32_e32 v0, v8, v171
	s_movk_i32 s12, 0x5800
	v_mad_i64_i32 v[0:1], s[2:3], v0, s12, v[16:17]
	global_load_dwordx4 v[0:3], v[0:1], off
	v_add_u32_e32 v64, v8, v199
	v_mad_i64_i32 v[64:65], s[2:3], v64, s12, v[16:17]
	global_load_dwordx4 v[64:67], v[64:65], off
	v_add_u32_e32 v5, v197, v198
	s_waitcnt vmcnt(1)
	v_cvt_pk_bf16_f32 v0, v0, s0
	ds_write_b16 v5, v0
	v_cvt_pk_bf16_f32 v0, v1, s0
	ds_write_b16 v5, v0 offset:132
	v_cvt_pk_bf16_f32 v0, v2, s0
	ds_write_b16 v5, v0 offset:264
	v_cvt_pk_bf16_f32 v0, v3, s0
	ds_write_b16 v5, v0 offset:396
	v_add_u32_e32 v5, v200, v198
	s_waitcnt vmcnt(0)
	v_cvt_pk_bf16_f32 v0, v64, s0
	ds_write_b16 v5, v0
	v_cvt_pk_bf16_f32 v0, v65, s0
	ds_write_b16 v5, v0 offset:132
	v_cvt_pk_bf16_f32 v0, v66, s0
	ds_write_b16 v5, v0 offset:264
	v_cvt_pk_bf16_f32 v0, v67, s0
	ds_write_b16 v5, v0 offset:396

; __device__ __forceinline__ unsigned short f2bf(float f) { return (unsigned short)(pk2(f, 0.f) & 0xffffu); }
; __device__ __forceinline__ void cvt_tile(unsigned char* lds, const float* src, int ld, int n_begin, int K, bf16_t* dst, int Kd, int koff, int mode, int roff, int t, int tid) {
;     const int ntk = Kd / 64; unsigned short* tile = (unsigned short*)lds;
;     const int tn = t / ntk, tk = t - tn * ntk; const int n0 = tn * 64, k0 = tk * 64;
;     const bool valid = (src != nullptr) && (k0 >= koff) && (k0 < koff + K);
;     __syncthreads();
;     if (valid) {
; #pragma unroll
;         for (int it = 0; it < 2; ++it) { const int idx = tid + 512 * it, kr = idx >> 4, nc4 = idx & 15;
;             const f32x4 v = *(const f32x4*)(src + (size_t)(k0 - koff + kr) * ld + n_begin + n0 + 4 * nc4);
; #pragma unroll
;             for (int j = 0; j < 4; ++j) tile[(4 * nc4 + j) * 66 + kr] = f2bf(v[j]); }
;     }
; __device__ __forceinline__ void cvt_ffn_tile(unsigned char* lds, unsigned char* ws, const float* w_in, const float* w_out, int gt, int tid) {
;     bf16_t* WA = (bf16_t*)(ws + WS_WA); bf16_t* WB = (bf16_t*)(ws + WS_WB);
;     if (gt < 704) cvt_tile(lds, w_in, NFF, 0, DM, WA, DM, 0, 1, 0, gt, tid);
;     else if (gt < 1408) cvt_tile(lds, w_in, NFF, DFF, DM, WA, DM, 0, 1, 128, gt - 704, tid);
;     else cvt_tile(lds, w_out, DM, 0, DFF, WB, DFF, 0, 0, 0, gt - 1408, tid);
.LBB0_291:
	s_andn2_saveexec_b64 s[0:1], s[0:1]
	s_cbranch_execz .LBB0_297
	s_waitcnt lgkmcnt(1)
	v_lshl_or_b32 v0, v12, 9, v194
	v_sub_u32_e32 v8, v0, v14
	s_movk_i32 s2, 0x400
	v_cmp_gt_u32_e64 s[6:7], s2, v8
	s_and_b64 s[6:7], s[46:47], s[6:7]
	s_waitcnt lgkmcnt(0)
	s_barrier
	s_and_saveexec_b64 s[10:11], s[6:7]
	s_cbranch_execz .LBB0_294
	v_lshl_add_u64 v[10:11], v[112:113], 2, v[162:163]
	v_add_u32_e32 v0, v8, v171
	s_movk_i32 s12, 0x5800
	v_mad_i64_i32 v[0:1], s[2:3], v0, s12, v[10:11]
	global_load_dwordx4 v[0:3], v[0:1], off
	v_add_u32_e32 v64, v8, v199
	v_mad_i64_i32 v[64:65], s[2:3], v64, s12, v[10:11]
	global_load_dwordx4 v[64:67], v[64:65], off
	v_add_u32_e32 v5, v197, v198
	s_waitcnt vmcnt(1)
	v_cvt_pk_bf16_f32 v0, v0, s0
	ds_write_b16 v5, v0
	v_cvt_pk_bf16_f32 v0, v1, s0
	ds_write_b16 v5, v0 offset:132
	v_cvt_pk_bf16_f32 v0, v2, s0
	ds_write_b16 v5, v0 offset:264
	v_cvt_pk_bf16_f32 v0, v3, s0
	ds_write_b16 v5, v0 offset:396
	v_add_u32_e32 v5, v200, v198
	s_waitcnt vmcnt(0)
	v_cvt_pk_bf16_f32 v0, v64, s0
	ds_write_b16 v5, v0
	v_cvt_pk_bf16_f32 v0, v65, s0
	ds_write_b16 v5, v0 offset:132
	v_cvt_pk_bf16_f32 v0, v66, s0
	ds_write_b16 v5, v0 offset:264
	v_cvt_pk_bf16_f32 v0, v67, s0
	ds_write_b16 v5, v0 offset:396

; __device__ __forceinline__ unsigned short f2bf(float f) { return (unsigned short)(pk2(f, 0.f) & 0xffffu); }
; __device__ __forceinline__ void cvt_tile(unsigned char* lds, const float* src, int ld, int n_begin, int K, bf16_t* dst, int Kd, int koff, int mode, int roff, int t, int tid) {
;     const int ntk = Kd / 64; unsigned short* tile = (unsigned short*)lds;
;     const int tn = t / ntk, tk = t - tn * ntk; const int n0 = tn * 64, k0 = tk * 64;
;     const bool valid = (src != nullptr) && (k0 >= koff) && (k0 < koff + K);
;     __syncthreads();
;     if (valid) {
; #pragma unroll
;         for (int it = 0; it < 2; ++it) { const int idx = tid + 512 * it, kr = idx >> 4, nc4 = idx & 15;
;             const f32x4 v = *(const f32x4*)(src + (size_t)(k0 - koff + kr) * ld + n_begin + n0 + 4 * nc4);
; #pragma unroll
;             for (int j = 0; j < 4; ++j) tile[(4 * nc4 + j) * 66 + kr] = f2bf(v[j]); }
;     }
;     __syncthreads();
;     { const int n = tid >> 3, kc = (tid & 7) * 8; u32x4 w = (u32x4){0u, 0u, 0u, 0u};
;       if (valid) { const unsigned* tp = (const unsigned*)(tile + n * 66 + kc); w.x = tp[0]; w.y = tp[1]; w.z = tp[2]; w.w = tp[3]; }
;       const int nl = n0 + n; const int drow = (mode == 0) ? (nl + roff) : (256 * (nl >> 7) + (nl & 127) + roff);
;       *(u32x4*)(dst + (size_t)drow * Kd + k0 + kc) = w; }
; __device__ __forceinline__ void cvt_ffn_tile(unsigned char* lds, unsigned char* ws, const float* w_in, const float* w_out, int gt, int tid) {
;     bf16_t* WA = (bf16_t*)(ws + WS_WA); bf16_t* WB = (bf16_t*)(ws + WS_WB);
;     if (gt < 704) cvt_tile(lds, w_in, NFF, 0, DM, WA, DM, 0, 1, 0, gt, tid);
;     else if (gt < 1408) cvt_tile(lds, w_in, NFF, DFF, DM, WA, DM, 0, 1, 128, gt - 704, tid);
;     else cvt_tile(lds, w_out, DM, 0, DFF, WB, DFF, 0, 0, 0, gt - 1408, tid);
.LBB0_297:
	s_or_b64 exec, exec, s[0:1]
	v_ashrrev_i32_e32 v9, 31, v8
	v_lshl_add_u64 v[8:9], v[8:9], 1, v[10:11]
	v_mov_b32_e32 v5, v113
	v_lshl_add_u64 v[8:9], v[8:9], 0, v[4:5]
	s_waitcnt lgkmcnt(0)
	global_store_dwordx4 v[8:9], v[0:3], off
	s_and_saveexec_b64 s[0:1], vcc
	s_xor_b64 s[0:1], exec, s[0:1]
	s_cbranch_execz .LBB0_311
	s_movk_i32 s2, 0xaf
	v_cmp_lt_u32_e64 s[6:7], s2, v12
	s_and_saveexec_b64 s[2:3], s[6:7]
	s_xor_b64 s[10:11], exec, s[2:3]
	s_cbranch_execz .LBB0_304
	v_add_u32_e32 v0, 0xfffffa86, v13
	v_mul_u32_u24_e32 v1, 0xba2f, v0
	v_lshrrev_b32_e32 v1, 21, v1
	s_movk_i32 s2, 0xffd4
	v_mad_i32_i24 v0, v1, s2, v0
	v_cmp_gt_u32_e64 s[6:7], 44, v0
	v_lshlrev_b32_e32 v5, 6, v1
	v_lshlrev_b32_e32 v8, 6, v0
	s_and_b64 s[6:7], s[28:29], s[6:7]
	s_waitcnt vmcnt(63) expcnt(7) lgkmcnt(15)
	s_barrier
	s_and_saveexec_b64 s[16:17], s[6:7]
	s_cbranch_execz .LBB0_301
	v_lshlrev_b32_e32 v0, 2, v5
	v_mov_b32_e32 v1, v113
	v_lshl_add_u64 v[10:11], v[160:161], 0, v[0:1]
	v_add_u32_e32 v0, v8, v171
	v_ashrrev_i32_e32 v1, 31, v0
	v_lshlrev_b64 v[0:1], 12, v[0:1]
	v_lshl_add_u64 v[0:1], v[10:11], 0, v[0:1]
	global_load_dwordx4 v[0:3], v[0:1], off
	v_add_u32_e32 v64, v8, v199
	v_ashrrev_i32_e32 v65, 31, v64
	v_lshlrev_b64 v[64:65], 12, v[64:65]
	v_lshl_add_u64 v[64:65], v[10:11], 0, v[64:65]
	global_load_dwordx4 v[64:67], v[64:65], off
	v_add_u32_e32 v9, v197, v198
	s_waitcnt vmcnt(1)
	v_cvt_pk_bf16_f32 v0, v0, s0
	ds_write_b16 v9, v0
	v_cvt_pk_bf16_f32 v0, v1, s0
	ds_write_b16 v9, v0 offset:132
	v_cvt_pk_bf16_f32 v0, v2, s0
	ds_write_b16 v9, v0 offset:264
	v_cvt_pk_bf16_f32 v0, v3, s0
	ds_write_b16 v9, v0 offset:396
	v_add_u32_e32 v9, v200, v198
	s_waitcnt vmcnt(0)
	v_cvt_pk_bf16_f32 v0, v64, s0
	ds_write_b16 v9, v0
	v_cvt_pk_bf16_f32 v0, v65, s0
	ds_write_b16 v9, v0 offset:132
	v_cvt_pk_bf16_f32 v0, v66, s0
	ds_write_b16 v9, v0 offset:264
	v_cvt_pk_bf16_f32 v0, v67, s0
	ds_write_b16 v9, v0 offset:396

; __device__ __forceinline__ unsigned short f2bf(float f) { return (unsigned short)(pk2(f, 0.f) & 0xffffu); }
; __device__ __forceinline__ void cvt_tile(unsigned char* lds, const float* src, int ld, int n_begin, int K, bf16_t* dst, int Kd, int koff, int mode, int roff, int t, int tid) {
;     const int ntk = Kd / 64; unsigned short* tile = (unsigned short*)lds;
;     const int tn = t / ntk, tk = t - tn * ntk; const int n0 = tn * 64, k0 = tk * 64;
;     const bool valid = (src != nullptr) && (k0 >= koff) && (k0 < koff + K);
;     __syncthreads();
;     if (valid) {
; #pragma unroll
;         for (int it = 0; it < 2; ++it) { const int idx = tid + 512 * it, kr = idx >> 4, nc4 = idx & 15;
;             const f32x4 v = *(const f32x4*)(src + (size_t)(k0 - koff + kr) * ld + n_begin + n0 + 4 * nc4);
; #pragma unroll
;             for (int j = 0; j < 4; ++j) tile[(4 * nc4 + j) * 66 + kr] = f2bf(v[j]); }
;     }
; __device__ __forceinline__ void cvt_ffn_tile(unsigned char* lds, unsigned char* ws, const float* w_in, const float* w_out, int gt, int tid) {
;     bf16_t* WA = (bf16_t*)(ws + WS_WA); bf16_t* WB = (bf16_t*)(ws + WS_WB);
;     if (gt < 704) cvt_tile(lds, w_in, NFF, 0, DM, WA, DM, 0, 1, 0, gt, tid);
;     else if (gt < 1408) cvt_tile(lds, w_in, NFF, DFF, DM, WA, DM, 0, 1, 128, gt - 704, tid);
;     else cvt_tile(lds, w_out, DM, 0, DFF, WB, DFF, 0, 0, 0, gt - 1408, tid);
.LBB0_304:
	s_andn2_saveexec_b64 s[10:11], s[10:11]
	s_cbranch_execz .LBB0_310
	s_waitcnt lgkmcnt(1)
	v_add_u32_e32 v0, 0xfffffd46, v13
	v_lshrrev_b32_e32 v1, 4, v0
	v_lshlrev_b32_e32 v10, 6, v1
	v_lshlrev_b32_e32 v1, 10, v1
	v_lshlrev_b32_e32 v0, 6, v0
	v_sub_u32_e32 v8, v0, v1
	s_movk_i32 s2, 0x400
	v_cmp_gt_u32_e64 s[6:7], s2, v8
	s_and_b64 s[6:7], s[46:47], s[6:7]
	s_waitcnt lgkmcnt(0)
	s_barrier
	s_and_saveexec_b64 s[16:17], s[6:7]
	s_cbranch_execz .LBB0_307
	v_mov_b32_e32 v11, v113
	v_lshl_add_u64 v[16:17], v[10:11], 2, v[164:165]
	v_add_u32_e32 v0, v8, v171
	s_movk_i32 s12, 0x5800
	v_mad_i64_i32 v[0:1], s[2:3], v0, s12, v[16:17]
	global_load_dwordx4 v[0:3], v[0:1], off
	v_add_u32_e32 v64, v8, v199
	v_mad_i64_i32 v[64:65], s[2:3], v64, s12, v[16:17]
	global_load_dwordx4 v[64:67], v[64:65], off
	v_add_u32_e32 v5, v197, v198
	s_waitcnt vmcnt(1)
	v_cvt_pk_bf16_f32 v0, v0, s0
	ds_write_b16 v5, v0
	v_cvt_pk_bf16_f32 v0, v1, s0
	ds_write_b16 v5, v0 offset:132
	v_cvt_pk_bf16_f32 v0, v2, s0
	ds_write_b16 v5, v0 offset:264
	v_cvt_pk_bf16_f32 v0, v3, s0
	ds_write_b16 v5, v0 offset:396
	v_add_u32_e32 v5, v200, v198
	s_waitcnt vmcnt(0)
	v_cvt_pk_bf16_f32 v0, v64, s0
	ds_write_b16 v5, v0
	v_cvt_pk_bf16_f32 v0, v65, s0
	ds_write_b16 v5, v0 offset:132
	v_cvt_pk_bf16_f32 v0, v66, s0
	ds_write_b16 v5, v0 offset:264
	v_cvt_pk_bf16_f32 v0, v67, s0
	ds_write_b16 v5, v0 offset:396

; __device__ __forceinline__ unsigned short f2bf(float f) { return (unsigned short)(pk2(f, 0.f) & 0xffffu); }
; __device__ __forceinline__ void cvt_tile(unsigned char* lds, const float* src, int ld, int n_begin, int K, bf16_t* dst, int Kd, int koff, int mode, int roff, int t, int tid) {
;     const int ntk = Kd / 64; unsigned short* tile = (unsigned short*)lds;
;     const int tn = t / ntk, tk = t - tn * ntk; const int n0 = tn * 64, k0 = tk * 64;
;     const bool valid = (src != nullptr) && (k0 >= koff) && (k0 < koff + K);
;     __syncthreads();
;     if (valid) {
; #pragma unroll
;         for (int it = 0; it < 2; ++it) { const int idx = tid + 512 * it, kr = idx >> 4, nc4 = idx & 15;
;             const f32x4 v = *(const f32x4*)(src + (size_t)(k0 - koff + kr) * ld + n_begin + n0 + 4 * nc4);
; #pragma unroll
;             for (int j = 0; j < 4; ++j) tile[(4 * nc4 + j) * 66 + kr] = f2bf(v[j]); }
;     }
; __device__ __forceinline__ void cvt_ffn_tile(unsigned char* lds, unsigned char* ws, const float* w_in, const float* w_out, int gt, int tid) {
;     bf16_t* WA = (bf16_t*)(ws + WS_WA); bf16_t* WB = (bf16_t*)(ws + WS_WB);
;     if (gt < 704) cvt_tile(lds, w_in, NFF, 0, DM, WA, DM, 0, 1, 0, gt, tid);
;     else if (gt < 1408) cvt_tile(lds, w_in, NFF, DFF, DM, WA, DM, 0, 1, 128, gt - 704, tid);
;     else cvt_tile(lds, w_out, DM, 0, DFF, WB, DFF, 0, 0, 0, gt - 1408, tid);
.LBB0_311:
	s_andn2_saveexec_b64 s[0:1], s[0:1]
	s_cbranch_execz .LBB0_317
	s_waitcnt lgkmcnt(1)
	v_lshl_or_b32 v0, v12, 9, v195
	v_sub_u32_e32 v8, v0, v14
	s_movk_i32 s2, 0x400
	v_cmp_gt_u32_e64 s[6:7], s2, v8
	s_and_b64 s[6:7], s[46:47], s[6:7]
	s_waitcnt lgkmcnt(0)
	s_barrier
	s_and_saveexec_b64 s[10:11], s[6:7]
	s_cbranch_execz .LBB0_314
	v_lshl_add_u64 v[10:11], v[112:113], 2, v[162:163]
	v_add_u32_e32 v0, v8, v171
	s_movk_i32 s12, 0x5800
	v_mad_i64_i32 v[0:1], s[2:3], v0, s12, v[10:11]
	global_load_dwordx4 v[0:3], v[0:1], off
	v_add_u32_e32 v64, v8, v199
	v_mad_i64_i32 v[64:65], s[2:3], v64, s12, v[10:11]
	global_load_dwordx4 v[64:67], v[64:65], off
	v_add_u32_e32 v5, v197, v198
	s_waitcnt vmcnt(1)
	v_cvt_pk_bf16_f32 v0, v0, s0
	ds_write_b16 v5, v0
	v_cvt_pk_bf16_f32 v0, v1, s0
	ds_write_b16 v5, v0 offset:132
	v_cvt_pk_bf16_f32 v0, v2, s0
	ds_write_b16 v5, v0 offset:264
	v_cvt_pk_bf16_f32 v0, v3, s0
	ds_write_b16 v5, v0 offset:396
	v_add_u32_e32 v5, v200, v198
	s_waitcnt vmcnt(0)
	v_cvt_pk_bf16_f32 v0, v64, s0
	ds_write_b16 v5, v0
	v_cvt_pk_bf16_f32 v0, v65, s0
	ds_write_b16 v5, v0 offset:132
	v_cvt_pk_bf16_f32 v0, v66, s0
	ds_write_b16 v5, v0 offset:264
	v_cvt_pk_bf16_f32 v0, v67, s0
	ds_write_b16 v5, v0 offset:396

; __device__ __forceinline__ unsigned short f2bf(float f) { return (unsigned short)(pk2(f, 0.f) & 0xffffu); }
; __device__ __forceinline__ void cvt_tile(unsigned char* lds, const float* src, int ld, int n_begin, int K, bf16_t* dst, int Kd, int koff, int mode, int roff, int t, int tid) {
;     const int ntk = Kd / 64; unsigned short* tile = (unsigned short*)lds;
;     const int tn = t / ntk, tk = t - tn * ntk; const int n0 = tn * 64, k0 = tk * 64;
;     const bool valid = (src != nullptr) && (k0 >= koff) && (k0 < koff + K);
;     __syncthreads();
;     if (valid) {
; #pragma unroll
;         for (int it = 0; it < 2; ++it) { const int idx = tid + 512 * it, kr = idx >> 4, nc4 = idx & 15;
;             const f32x4 v = *(const f32x4*)(src + (size_t)(k0 - koff + kr) * ld + n_begin + n0 + 4 * nc4);
; #pragma unroll
;             for (int j = 0; j < 4; ++j) tile[(4 * nc4 + j) * 66 + kr] = f2bf(v[j]); }
;     }
;     __syncthreads();
;     { const int n = tid >> 3, kc = (tid & 7) * 8; u32x4 w = (u32x4){0u, 0u, 0u, 0u};
;       if (valid) { const unsigned* tp = (const unsigned*)(tile + n * 66 + kc); w.x = tp[0]; w.y = tp[1]; w.z = tp[2]; w.w = tp[3]; }
;       const int nl = n0 + n; const int drow = (mode == 0) ? (nl + roff) : (256 * (nl >> 7) + (nl & 127) + roff);
;       *(u32x4*)(dst + (size_t)drow * Kd + k0 + kc) = w; }
; __device__ __forceinline__ void cvt_ffn_tile(unsigned char* lds, unsigned char* ws, const float* w_in, const float* w_out, int gt, int tid) {
;     bf16_t* WA = (bf16_t*)(ws + WS_WA); bf16_t* WB = (bf16_t*)(ws + WS_WB);
;     if (gt < 704) cvt_tile(lds, w_in, NFF, 0, DM, WA, DM, 0, 1, 0, gt, tid);
;     else if (gt < 1408) cvt_tile(lds, w_in, NFF, DFF, DM, WA, DM, 0, 1, 128, gt - 704, tid);
;     else cvt_tile(lds, w_out, DM, 0, DFF, WB, DFF, 0, 0, 0, gt - 1408, tid);
.LBB0_317:
	s_or_b64 exec, exec, s[0:1]
	v_ashrrev_i32_e32 v9, 31, v8
	v_lshl_add_u64 v[8:9], v[8:9], 1, v[10:11]
	v_mov_b32_e32 v5, v113
	v_lshl_add_u64 v[8:9], v[8:9], 0, v[4:5]
	s_waitcnt lgkmcnt(0)
	global_store_dwordx4 v[8:9], v[0:3], off
	s_and_saveexec_b64 s[0:1], vcc
	s_xor_b64 s[0:1], exec, s[0:1]
	s_cbranch_execz .LBB0_331
	s_movk_i32 s2, 0xaf
	v_cmp_lt_u32_e32 vcc, s2, v12
	s_and_saveexec_b64 s[2:3], vcc
	s_xor_b64 s[6:7], exec, s[2:3]
	s_cbranch_execz .LBB0_324
	v_add_u32_e32 v0, 0xfffffa87, v13
	v_mul_u32_u24_e32 v1, 0xba2f, v0
	v_lshrrev_b32_e32 v1, 21, v1
	s_movk_i32 s2, 0xffd4
	v_mad_i32_i24 v0, v1, s2, v0
	v_cmp_gt_u32_e32 vcc, 44, v0
	v_lshlrev_b32_e32 v5, 6, v1
	v_lshlrev_b32_e32 v8, 6, v0
	s_and_b64 s[10:11], s[28:29], vcc
	s_waitcnt vmcnt(63) expcnt(7) lgkmcnt(15)
	s_barrier
	s_and_saveexec_b64 s[16:17], s[10:11]
	s_cbranch_execz .LBB0_321
	v_add_u32_e32 v0, v8, v171
	v_lshlrev_b32_e32 v112, 2, v5
	v_ashrrev_i32_e32 v1, 31, v0
	v_lshl_add_u64 v[6:7], v[160:161], 0, v[112:113]
	v_lshlrev_b64 v[0:1], 12, v[0:1]
	v_lshl_add_u64 v[0:1], v[6:7], 0, v[0:1]
	global_load_dwordx4 v[0:3], v[0:1], off
	v_add_u32_e32 v64, v8, v199
	v_ashrrev_i32_e32 v65, 31, v64
	v_lshlrev_b64 v[64:65], 12, v[64:65]
	v_lshl_add_u64 v[64:65], v[6:7], 0, v[64:65]
	global_load_dwordx4 v[64:67], v[64:65], off
	v_add_u32_e32 v9, v197, v198
	s_waitcnt vmcnt(1)
	v_cvt_pk_bf16_f32 v0, v0, s0
	ds_write_b16 v9, v0
	v_cvt_pk_bf16_f32 v0, v1, s0
	ds_write_b16 v9, v0 offset:132
	v_cvt_pk_bf16_f32 v0, v2, s0
	ds_write_b16 v9, v0 offset:264
	v_cvt_pk_bf16_f32 v0, v3, s0
	ds_write_b16 v9, v0 offset:396
	v_add_u32_e32 v6, v200, v198
	s_waitcnt vmcnt(0)
	v_cvt_pk_bf16_f32 v0, v64, s0
	ds_write_b16 v6, v0
	v_cvt_pk_bf16_f32 v0, v65, s0
	ds_write_b16 v6, v0 offset:132
	v_cvt_pk_bf16_f32 v0, v66, s0
	ds_write_b16 v6, v0 offset:264
	v_cvt_pk_bf16_f32 v0, v67, s0
	ds_write_b16 v6, v0 offset:396

; __device__ __forceinline__ unsigned short f2bf(float f) { return (unsigned short)(pk2(f, 0.f) & 0xffffu); }
; __device__ __forceinline__ void cvt_tile(unsigned char* lds, const float* src, int ld, int n_begin, int K, bf16_t* dst, int Kd, int koff, int mode, int roff, int t, int tid) {
;     const int ntk = Kd / 64; unsigned short* tile = (unsigned short*)lds;
;     const int tn = t / ntk, tk = t - tn * ntk; const int n0 = tn * 64, k0 = tk * 64;
;     const bool valid = (src != nullptr) && (k0 >= koff) && (k0 < koff + K);
;     __syncthreads();
;     if (valid) {
; #pragma unroll
;         for (int it = 0; it < 2; ++it) { const int idx = tid + 512 * it, kr = idx >> 4, nc4 = idx & 15;
;             const f32x4 v = *(const f32x4*)(src + (size_t)(k0 - koff + kr) * ld + n_begin + n0 + 4 * nc4);
; #pragma unroll
;             for (int j = 0; j < 4; ++j) tile[(4 * nc4 + j) * 66 + kr] = f2bf(v[j]); }
;     }
; __device__ __forceinline__ void cvt_ffn_tile(unsigned char* lds, unsigned char* ws, const float* w_in, const float* w_out, int gt, int tid) {
;     bf16_t* WA = (bf16_t*)(ws + WS_WA); bf16_t* WB = (bf16_t*)(ws + WS_WB);
;     if (gt < 704) cvt_tile(lds, w_in, NFF, 0, DM, WA, DM, 0, 1, 0, gt, tid);
;     else if (gt < 1408) cvt_tile(lds, w_in, NFF, DFF, DM, WA, DM, 0, 1, 128, gt - 704, tid);
;     else cvt_tile(lds, w_out, DM, 0, DFF, WB, DFF, 0, 0, 0, gt - 1408, tid);
.LBB0_324:
	s_andn2_saveexec_b64 s[6:7], s[6:7]
	s_cbranch_execz .LBB0_330
	s_waitcnt lgkmcnt(1)
	v_add_u32_e32 v0, 0xfffffd47, v13
	v_lshrrev_b32_e32 v1, 4, v0
	v_lshlrev_b32_e32 v112, 6, v1
	v_lshlrev_b32_e32 v1, 10, v1
	v_lshlrev_b32_e32 v0, 6, v0
	v_sub_u32_e32 v8, v0, v1
	s_movk_i32 s2, 0x400
	v_cmp_gt_u32_e32 vcc, s2, v8
	s_and_b64 s[10:11], s[46:47], vcc
	s_waitcnt lgkmcnt(0)
	s_barrier
	s_and_saveexec_b64 s[16:17], s[10:11]
	s_cbranch_execz .LBB0_327
	v_lshl_add_u64 v[6:7], v[112:113], 2, v[164:165]
	v_add_u32_e32 v0, v8, v171
	s_movk_i32 s12, 0x5800
	v_mad_i64_i32 v[0:1], s[2:3], v0, s12, v[6:7]
	global_load_dwordx4 v[0:3], v[0:1], off
	v_add_u32_e32 v64, v8, v199
	v_mad_i64_i32 v[64:65], s[2:3], v64, s12, v[6:7]
	global_load_dwordx4 v[64:67], v[64:65], off
	v_add_u32_e32 v5, v197, v198
	s_waitcnt vmcnt(1)
	v_cvt_pk_bf16_f32 v0, v0, s0
	ds_write_b16 v5, v0
	v_cvt_pk_bf16_f32 v0, v1, s0
	ds_write_b16 v5, v0 offset:132
	v_cvt_pk_bf16_f32 v0, v2, s0
	ds_write_b16 v5, v0 offset:264
	v_cvt_pk_bf16_f32 v0, v3, s0
	ds_write_b16 v5, v0 offset:396
	v_add_u32_e32 v5, v200, v198
	s_waitcnt vmcnt(0)
	v_cvt_pk_bf16_f32 v0, v64, s0
	ds_write_b16 v5, v0
	v_cvt_pk_bf16_f32 v0, v65, s0
	ds_write_b16 v5, v0 offset:132
	v_cvt_pk_bf16_f32 v0, v66, s0
	ds_write_b16 v5, v0 offset:264
	v_cvt_pk_bf16_f32 v0, v67, s0
	ds_write_b16 v5, v0 offset:396

; __device__ __forceinline__ unsigned short f2bf(float f) { return (unsigned short)(pk2(f, 0.f) & 0xffffu); }
; __device__ __forceinline__ void cvt_tile(unsigned char* lds, const float* src, int ld, int n_begin, int K, bf16_t* dst, int Kd, int koff, int mode, int roff, int t, int tid) {
;     const int ntk = Kd / 64; unsigned short* tile = (unsigned short*)lds;
;     const int tn = t / ntk, tk = t - tn * ntk; const int n0 = tn * 64, k0 = tk * 64;
;     const bool valid = (src != nullptr) && (k0 >= koff) && (k0 < koff + K);
;     __syncthreads();
;     if (valid) {
; #pragma unroll
;         for (int it = 0; it < 2; ++it) { const int idx = tid + 512 * it, kr = idx >> 4, nc4 = idx & 15;
;             const f32x4 v = *(const f32x4*)(src + (size_t)(k0 - koff + kr) * ld + n_begin + n0 + 4 * nc4);
; #pragma unroll
;             for (int j = 0; j < 4; ++j) tile[(4 * nc4 + j) * 66 + kr] = f2bf(v[j]); }
;     }
; __device__ __forceinline__ void cvt_ffn_tile(unsigned char* lds, unsigned char* ws, const float* w_in, const float* w_out, int gt, int tid) {
;     bf16_t* WA = (bf16_t*)(ws + WS_WA); bf16_t* WB = (bf16_t*)(ws + WS_WB);
;     if (gt < 704) cvt_tile(lds, w_in, NFF, 0, DM, WA, DM, 0, 1, 0, gt, tid);
;     else if (gt < 1408) cvt_tile(lds, w_in, NFF, DFF, DM, WA, DM, 0, 1, 128, gt - 704, tid);
;     else cvt_tile(lds, w_out, DM, 0, DFF, WB, DFF, 0, 0, 0, gt - 1408, tid);
.LBB0_331:
	s_andn2_saveexec_b64 s[0:1], s[0:1]
	s_cbranch_execz .LBB0_139
	s_waitcnt lgkmcnt(1)
	v_lshl_or_b32 v0, v12, 9, v196
	v_sub_u32_e32 v8, v0, v14
	s_movk_i32 s2, 0x400
	v_cmp_gt_u32_e32 vcc, s2, v8
	s_and_b64 s[6:7], s[46:47], vcc
	s_waitcnt lgkmcnt(0)
	s_barrier
	s_and_saveexec_b64 s[10:11], s[6:7]
	s_cbranch_execz .LBB0_334
	v_lshl_add_u64 v[10:11], v[112:113], 2, v[162:163]
	v_add_u32_e32 v0, v8, v171
	s_movk_i32 s12, 0x5800
	v_mad_i64_i32 v[0:1], s[2:3], v0, s12, v[10:11]
	global_load_dwordx4 v[0:3], v[0:1], off
	v_add_u32_e32 v64, v8, v199
	v_mad_i64_i32 v[64:65], s[2:3], v64, s12, v[10:11]
	global_load_dwordx4 v[64:67], v[64:65], off
	v_add_u32_e32 v5, v197, v198
	s_waitcnt vmcnt(1)
	v_cvt_pk_bf16_f32 v0, v0, s0
	ds_write_b16 v5, v0
	v_cvt_pk_bf16_f32 v0, v1, s0
	ds_write_b16 v5, v0 offset:132
	v_cvt_pk_bf16_f32 v0, v2, s0
	ds_write_b16 v5, v0 offset:264
	v_cvt_pk_bf16_f32 v0, v3, s0
	ds_write_b16 v5, v0 offset:396
	v_add_u32_e32 v5, v200, v198
	s_waitcnt vmcnt(0)
	v_cvt_pk_bf16_f32 v0, v64, s0
	ds_write_b16 v5, v0
	v_cvt_pk_bf16_f32 v0, v65, s0
	ds_write_b16 v5, v0 offset:132
	v_cvt_pk_bf16_f32 v0, v66, s0
	ds_write_b16 v5, v0 offset:264
	v_cvt_pk_bf16_f32 v0, v67, s0
	ds_write_b16 v5, v0 offset:396

; __device__ __forceinline__ unsigned short f2bf(float f) { return (unsigned short)(pk2(f, 0.f) & 0xffffu); }
; __device__ __forceinline__ void cvt_tile(unsigned char* lds, const float* src, int ld, int n_begin, int K, bf16_t* dst, int Kd, int koff, int mode, int roff, int t, int tid) {
;     const int ntk = Kd / 64; unsigned short* tile = (unsigned short*)lds;
;     const int tn = t / ntk, tk = t - tn * ntk; const int n0 = tn * 64, k0 = tk * 64;
;     const bool valid = (src != nullptr) && (k0 >= koff) && (k0 < koff + K);
;     __syncthreads();
;     if (valid) {
; #pragma unroll
;         for (int it = 0; it < 2; ++it) { const int idx = tid + 512 * it, kr = idx >> 4, nc4 = idx & 15;
;             const f32x4 v = *(const f32x4*)(src + (size_t)(k0 - koff + kr) * ld + n_begin + n0 + 4 * nc4);
; #pragma unroll
;             for (int j = 0; j < 4; ++j) tile[(4 * nc4 + j) * 66 + kr] = f2bf(v[j]); }
;     }
.LBB0_660:
	s_ashr_i32 s4, s2, 31
	s_lshr_b32 s4, s4, 28
	s_add_i32 s4, s2, s4
	s_ashr_i32 s4, s4, 4
	s_lshl_b32 s7, s4, 10
	s_lshl_b32 s8, s4, 6
	s_sub_i32 s6, s3, s7
	s_cmpk_lt_u32 s6, 0x400
	s_cselect_b64 s[4:5], -1, 0
	s_and_b64 s[10:11], s[12:13], s[4:5]
	v_cndmask_b32_e64 v0, 0, 1, s[10:11]
	v_cmp_ne_u32_e64 s[4:5], 1, v0
	s_andn2_b64 vcc, exec, s[10:11]
	s_barrier
	s_cbranch_vccnz .LBB0_662
	s_sub_i32 s7, 0, s7
	s_ashr_i32 s9, s8, 31
	s_add_i32 s7, s7, s3
	v_lshl_add_u64 v[12:13], s[8:9], 2, v[4:5]
	v_add_u32_e32 v0, s7, v6
	s_movk_i32 s9, 0x5600
	v_mad_i64_i32 v[0:1], s[10:11], v0, s9, v[12:13]
	global_load_dwordx4 v[0:3], v[0:1], off
	v_add_u32_e32 v64, s7, v7
	v_mad_i64_i32 v[64:65], s[10:11], v64, s9, v[12:13]
	global_load_dwordx4 v[64:67], v[64:65], off
	s_waitcnt vmcnt(1)
	v_cvt_pk_bf16_f32 v0, v0, s0
	ds_write_b16 v10, v0
	v_cvt_pk_bf16_f32 v0, v1, s0
	ds_write_b16 v10, v0 offset:132
	v_cvt_pk_bf16_f32 v0, v2, s0
	ds_write_b16 v10, v0 offset:264
	v_cvt_pk_bf16_f32 v0, v3, s0
	ds_write_b16 v10, v0 offset:396
	s_waitcnt vmcnt(0)
	v_cvt_pk_bf16_f32 v0, v64, s0
	ds_write_b16 v11, v0
	v_cvt_pk_bf16_f32 v0, v65, s0
	ds_write_b16 v11, v0 offset:132
	v_cvt_pk_bf16_f32 v0, v66, s0
	ds_write_b16 v11, v0 offset:264
	v_cvt_pk_bf16_f32 v0, v67, s0
	ds_write_b16 v11, v0 offset:396

; __device__ __forceinline__ unsigned short f2bf(float f) { return (unsigned short)(pk2(f, 0.f) & 0xffffu); }
; __device__ __forceinline__ void cvt_tile(unsigned char* lds, const float* src, int ld, int n_begin, int K, bf16_t* dst, int Kd, int koff, int mode, int roff, int t, int tid) {
;     const int ntk = Kd / 64; unsigned short* tile = (unsigned short*)lds;
;     const int tn = t / ntk, tk = t - tn * ntk; const int n0 = tn * 64, k0 = tk * 64;
;     const bool valid = (src != nullptr) && (k0 >= koff) && (k0 < koff + K);
;     __syncthreads();
;     if (valid) {
; #pragma unroll
;         for (int it = 0; it < 2; ++it) { const int idx = tid + 512 * it, kr = idx >> 4, nc4 = idx & 15;
;             const f32x4 v = *(const f32x4*)(src + (size_t)(k0 - koff + kr) * ld + n_begin + n0 + 4 * nc4);
; #pragma unroll
;             for (int j = 0; j < 4; ++j) tile[(4 * nc4 + j) * 66 + kr] = f2bf(v[j]); }
;     }
.LBB0_670:
	s_ashr_i32 s0, s2, 31
	s_lshr_b32 s0, s0, 28
	s_add_i32 s0, s2, s0
	s_ashr_i32 s0, s0, 4
	s_lshl_b32 s1, s0, 10
	s_lshl_b32 s6, s0, 6
	s_sub_i32 s0, s3, s1
	s_cmpk_lt_u32 s0, 0x400
	s_cselect_b64 s[4:5], -1, 0
	s_and_b64 s[8:9], s[12:13], s[4:5]
	v_cndmask_b32_e64 v0, 0, 1, s[8:9]
	v_cmp_ne_u32_e64 s[4:5], 1, v0
	s_andn2_b64 vcc, exec, s[8:9]
	s_barrier
	s_cbranch_vccnz .LBB0_672
	s_sub_i32 s1, 0, s1
	s_ashr_i32 s7, s6, 31
	s_add_i32 s1, s1, s3
	v_lshl_add_u64 v[12:13], s[6:7], 2, v[4:5]
	v_add_u32_e32 v0, s1, v6
	s_movk_i32 s7, 0x5600
	v_mad_i64_i32 v[0:1], s[8:9], v0, s7, v[12:13]
	global_load_dwordx4 v[0:3], v[0:1], off
	v_add_u32_e32 v64, s1, v7
	v_mad_i64_i32 v[64:65], s[8:9], v64, s7, v[12:13]
	global_load_dwordx4 v[64:67], v[64:65], off
	s_waitcnt vmcnt(1)
	v_cvt_pk_bf16_f32 v0, v0, s0
	ds_write_b16 v10, v0
	v_cvt_pk_bf16_f32 v0, v1, s0
	ds_write_b16 v10, v0 offset:132
	v_cvt_pk_bf16_f32 v0, v2, s0
	ds_write_b16 v10, v0 offset:264
	v_cvt_pk_bf16_f32 v0, v3, s0
	ds_write_b16 v10, v0 offset:396
	s_waitcnt vmcnt(0)
	v_cvt_pk_bf16_f32 v0, v64, s0
	ds_write_b16 v11, v0
	v_cvt_pk_bf16_f32 v0, v65, s0
	ds_write_b16 v11, v0 offset:132
	v_cvt_pk_bf16_f32 v0, v66, s0
	ds_write_b16 v11, v0 offset:264
	v_cvt_pk_bf16_f32 v0, v67, s0
	ds_write_b16 v11, v0 offset:396

; __device__ __forceinline__ unsigned short f2bf(float f) { return (unsigned short)(pk2(f, 0.f) & 0xffffu); }
; __device__ __forceinline__ void cvt_tile(unsigned char* lds, const float* src, int ld, int n_begin, int K, bf16_t* dst, int Kd, int koff, int mode, int roff, int t, int tid) {
;     const int ntk = Kd / 64; unsigned short* tile = (unsigned short*)lds;
;     const int tn = t / ntk, tk = t - tn * ntk; const int n0 = tn * 64, k0 = tk * 64;
;     const bool valid = (src != nullptr) && (k0 >= koff) && (k0 < koff + K);
;     __syncthreads();
;     if (valid) {
; #pragma unroll
;         for (int it = 0; it < 2; ++it) { const int idx = tid + 512 * it, kr = idx >> 4, nc4 = idx & 15;
;             const f32x4 v = *(const f32x4*)(src + (size_t)(k0 - koff + kr) * ld + n_begin + n0 + 4 * nc4);
; #pragma unroll
;             for (int j = 0; j < 4; ++j) tile[(4 * nc4 + j) * 66 + kr] = f2bf(v[j]); }
;     }
.LBB0_677:
	s_mul_hi_i32 s10, s2, 0x2aaaaaab
	s_lshr_b32 s4, s10, 31
	s_add_i32 s10, s10, s4
	s_mul_i32 s4, s10, 6
	s_lshl_b32 s8, s10, 6
	s_cmp_eq_u32 s4, s2
	s_cselect_b64 s[4:5], -1, 0
	s_and_b64 s[12:13], s[16:17], s[4:5]
	v_cndmask_b32_e64 v0, 0, 1, s[12:13]
	v_cmp_ne_u32_e64 s[4:5], 1, v0
	s_andn2_b64 vcc, exec, s[12:13]
	s_barrier
	s_cbranch_vccnz .LBB0_679
	s_ashr_i32 s9, s8, 31
	v_lshl_add_u64 v[14:15], s[8:9], 2, v[4:5]
	v_lshl_add_u64 v[0:1], v[14:15], 0, v[6:7]
	global_load_dwordx4 v[0:3], v[0:1], off
	v_lshl_add_u64 v[64:65], v[14:15], 0, v[8:9]
	global_load_dwordx4 v[64:67], v[64:65], off
	s_waitcnt vmcnt(1)
	v_cvt_pk_bf16_f32 v0, v0, s0
	ds_write_b16 v12, v0
	v_cvt_pk_bf16_f32 v0, v1, s0
	ds_write_b16 v12, v0 offset:132
	v_cvt_pk_bf16_f32 v0, v2, s0
	ds_write_b16 v12, v0 offset:264
	v_cvt_pk_bf16_f32 v0, v3, s0
	ds_write_b16 v12, v0 offset:396
	s_waitcnt vmcnt(0)
	v_cvt_pk_bf16_f32 v0, v64, s0
	ds_write_b16 v13, v0
	v_cvt_pk_bf16_f32 v0, v65, s0
	ds_write_b16 v13, v0 offset:132
	v_cvt_pk_bf16_f32 v0, v66, s0
	ds_write_b16 v13, v0 offset:264
	v_cvt_pk_bf16_f32 v0, v67, s0
	ds_write_b16 v13, v0 offset:396

; __device__ __forceinline__ unsigned short f2bf(float f) { return (unsigned short)(pk2(f, 0.f) & 0xffffu); }
; __device__ __forceinline__ void cvt_tile(unsigned char* lds, const float* src, int ld, int n_begin, int K, bf16_t* dst, int Kd, int koff, int mode, int roff, int t, int tid) {
;     const int ntk = Kd / 64; unsigned short* tile = (unsigned short*)lds;
;     const int tn = t / ntk, tk = t - tn * ntk; const int n0 = tn * 64, k0 = tk * 64;
;     const bool valid = (src != nullptr) && (k0 >= koff) && (k0 < koff + K);
;     __syncthreads();
;     if (valid) {
; #pragma unroll
;         for (int it = 0; it < 2; ++it) { const int idx = tid + 512 * it, kr = idx >> 4, nc4 = idx & 15;
;             const f32x4 v = *(const f32x4*)(src + (size_t)(k0 - koff + kr) * ld + n_begin + n0 + 4 * nc4);
; #pragma unroll
;             for (int j = 0; j < 4; ++j) tile[(4 * nc4 + j) * 66 + kr] = f2bf(v[j]); }
;     }
.LBB0_684:
	s_mul_hi_i32 s8, s2, 0x2aaaaaab
	s_lshr_b32 s4, s8, 31
	s_add_i32 s8, s8, s4
	s_mul_i32 s4, s8, 6
	s_or_b32 s5, s4, 1
	s_lshl_b32 s4, s8, 6
	s_cmp_eq_u32 s5, s2
	s_cselect_b64 s[6:7], -1, 0
	s_cmp_lg_u32 s5, s2
	s_barrier
	s_cbranch_scc1 .LBB0_686
	s_ashr_i32 s5, s4, 31
	v_lshl_add_u64 v[14:15], s[4:5], 2, v[4:5]
	v_lshl_add_u64 v[0:1], v[14:15], 0, v[6:7]
	global_load_dwordx4 v[0:3], v[0:1], off
	v_lshl_add_u64 v[64:65], v[14:15], 0, v[8:9]
	global_load_dwordx4 v[64:67], v[64:65], off
	s_waitcnt vmcnt(1)
	v_cvt_pk_bf16_f32 v0, v0, s0
	ds_write_b16 v12, v0
	v_cvt_pk_bf16_f32 v0, v1, s0
	ds_write_b16 v12, v0 offset:132
	v_cvt_pk_bf16_f32 v0, v2, s0
	ds_write_b16 v12, v0 offset:264
	v_cvt_pk_bf16_f32 v0, v3, s0
	ds_write_b16 v12, v0 offset:396
	s_waitcnt vmcnt(0)
	v_cvt_pk_bf16_f32 v0, v64, s0
	ds_write_b16 v13, v0
	v_cvt_pk_bf16_f32 v0, v65, s0
	ds_write_b16 v13, v0 offset:132
	v_cvt_pk_bf16_f32 v0, v66, s0
	ds_write_b16 v13, v0 offset:264
	v_cvt_pk_bf16_f32 v0, v67, s0
	ds_write_b16 v13, v0 offset:396

; __device__ __forceinline__ unsigned short f2bf(float f) { return (unsigned short)(pk2(f, 0.f) & 0xffffu); }
; __device__ __forceinline__ void cvt_tile(unsigned char* lds, const float* src, int ld, int n_begin, int K, bf16_t* dst, int Kd, int koff, int mode, int roff, int t, int tid) {
;     const int ntk = Kd / 64; unsigned short* tile = (unsigned short*)lds;
;     const int tn = t / ntk, tk = t - tn * ntk; const int n0 = tn * 64, k0 = tk * 64;
;     const bool valid = (src != nullptr) && (k0 >= koff) && (k0 < koff + K);
;     __syncthreads();
;     if (valid) {
; #pragma unroll
;         for (int it = 0; it < 2; ++it) { const int idx = tid + 512 * it, kr = idx >> 4, nc4 = idx & 15;
;             const f32x4 v = *(const f32x4*)(src + (size_t)(k0 - koff + kr) * ld + n_begin + n0 + 4 * nc4);
; #pragma unroll
;             for (int j = 0; j < 4; ++j) tile[(4 * nc4 + j) * 66 + kr] = f2bf(v[j]); }
;     }
.LBB0_691:
	s_mul_hi_i32 s10, s2, 0x2aaaaaab
	s_lshr_b32 s4, s10, 31
	s_add_i32 s10, s10, s4
	s_mul_i32 s4, s10, 6
	s_add_i32 s4, s4, 2
	s_lshl_b32 s8, s10, 6
	s_cmp_eq_u32 s4, s2
	s_cselect_b64 s[4:5], -1, 0
	s_and_b64 s[12:13], s[18:19], s[4:5]
	v_cndmask_b32_e64 v0, 0, 1, s[12:13]
	v_cmp_ne_u32_e64 s[4:5], 1, v0
	s_andn2_b64 vcc, exec, s[12:13]
	s_barrier
	s_cbranch_vccnz .LBB0_693
	s_ashr_i32 s9, s8, 31
	v_lshl_add_u64 v[14:15], s[8:9], 2, v[4:5]
	v_lshl_add_u64 v[0:1], v[14:15], 0, v[6:7]
	global_load_dwordx4 v[0:3], v[0:1], off
	v_lshl_add_u64 v[64:65], v[14:15], 0, v[8:9]
	global_load_dwordx4 v[64:67], v[64:65], off
	s_waitcnt vmcnt(1)
	v_cvt_pk_bf16_f32 v0, v0, s0
	ds_write_b16 v12, v0
	v_cvt_pk_bf16_f32 v0, v1, s0
	ds_write_b16 v12, v0 offset:132
	v_cvt_pk_bf16_f32 v0, v2, s0
	ds_write_b16 v12, v0 offset:264
	v_cvt_pk_bf16_f32 v0, v3, s0
	ds_write_b16 v12, v0 offset:396
	s_waitcnt vmcnt(0)
	v_cvt_pk_bf16_f32 v0, v64, s0
	ds_write_b16 v13, v0
	v_cvt_pk_bf16_f32 v0, v65, s0
	ds_write_b16 v13, v0 offset:132
	v_cvt_pk_bf16_f32 v0, v66, s0
	ds_write_b16 v13, v0 offset:264
	v_cvt_pk_bf16_f32 v0, v67, s0
	ds_write_b16 v13, v0 offset:396

; __device__ __forceinline__ unsigned short f2bf(float f) { return (unsigned short)(pk2(f, 0.f) & 0xffffu); }
; __device__ __forceinline__ void cvt_tile(unsigned char* lds, const float* src, int ld, int n_begin, int K, bf16_t* dst, int Kd, int koff, int mode, int roff, int t, int tid) {
;     const int ntk = Kd / 64; unsigned short* tile = (unsigned short*)lds;
;     const int tn = t / ntk, tk = t - tn * ntk; const int n0 = tn * 64, k0 = tk * 64;
;     const bool valid = (src != nullptr) && (k0 >= koff) && (k0 < koff + K);
;     __syncthreads();
;     if (valid) {
; #pragma unroll
;         for (int it = 0; it < 2; ++it) { const int idx = tid + 512 * it, kr = idx >> 4, nc4 = idx & 15;
;             const f32x4 v = *(const f32x4*)(src + (size_t)(k0 - koff + kr) * ld + n_begin + n0 + 4 * nc4);
; #pragma unroll
;             for (int j = 0; j < 4; ++j) tile[(4 * nc4 + j) * 66 + kr] = f2bf(v[j]); }
;     }
.LBB0_698:
	s_mul_hi_i32 s8, s2, 0x2aaaaaab
	s_lshr_b32 s4, s8, 31
	s_add_i32 s8, s8, s4
	s_mul_i32 s4, s8, 6
	s_add_i32 s5, s4, 3
	s_lshl_b32 s4, s8, 6
	s_cmp_eq_u32 s5, s2
	s_cselect_b64 s[6:7], -1, 0
	s_cmp_lg_u32 s5, s2
	s_barrier
	s_cbranch_scc1 .LBB0_700
	s_ashr_i32 s5, s4, 31
	v_lshl_add_u64 v[14:15], s[4:5], 2, v[4:5]
	v_lshl_add_u64 v[0:1], v[14:15], 0, v[6:7]
	global_load_dwordx4 v[0:3], v[0:1], off
	v_lshl_add_u64 v[64:65], v[14:15], 0, v[8:9]
	global_load_dwordx4 v[64:67], v[64:65], off
	s_waitcnt vmcnt(1)
	v_cvt_pk_bf16_f32 v0, v0, s0
	ds_write_b16 v12, v0
	v_cvt_pk_bf16_f32 v0, v1, s0
	ds_write_b16 v12, v0 offset:132
	v_cvt_pk_bf16_f32 v0, v2, s0
	ds_write_b16 v12, v0 offset:264
	v_cvt_pk_bf16_f32 v0, v3, s0
	ds_write_b16 v12, v0 offset:396
	s_waitcnt vmcnt(0)
	v_cvt_pk_bf16_f32 v0, v64, s0
	ds_write_b16 v13, v0
	v_cvt_pk_bf16_f32 v0, v65, s0
	ds_write_b16 v13, v0 offset:132
	v_cvt_pk_bf16_f32 v0, v66, s0
	ds_write_b16 v13, v0 offset:264
	v_cvt_pk_bf16_f32 v0, v67, s0
	ds_write_b16 v13, v0 offset:396

; __device__ __forceinline__ unsigned short f2bf(float f) { return (unsigned short)(pk2(f, 0.f) & 0xffffu); }
; __device__ __forceinline__ void cvt_tile(unsigned char* lds, const float* src, int ld, int n_begin, int K, bf16_t* dst, int Kd, int koff, int mode, int roff, int t, int tid) {
;     const int ntk = Kd / 64; unsigned short* tile = (unsigned short*)lds;
;     const int tn = t / ntk, tk = t - tn * ntk; const int n0 = tn * 64, k0 = tk * 64;
;     const bool valid = (src != nullptr) && (k0 >= koff) && (k0 < koff + K);
;     __syncthreads();
;     if (valid) {
; #pragma unroll
;         for (int it = 0; it < 2; ++it) { const int idx = tid + 512 * it, kr = idx >> 4, nc4 = idx & 15;
;             const f32x4 v = *(const f32x4*)(src + (size_t)(k0 - koff + kr) * ld + n_begin + n0 + 4 * nc4);
; #pragma unroll
;             for (int j = 0; j < 4; ++j) tile[(4 * nc4 + j) * 66 + kr] = f2bf(v[j]); }
;     }
.LBB0_705:
	s_mul_hi_i32 s0, s2, 0x2aaaaaab
	s_lshr_b32 s1, s0, 31
	s_add_i32 s6, s0, s1
	s_mul_i32 s0, s6, -6
	s_add_i32 s1, s2, s0
	s_lshl_b32 s0, s6, 6
	s_and_b32 s1, s1, -2
	s_cmp_eq_u32 s1, 4
	v_readlane_b32 s8, v252, 56
	s_cselect_b64 s[4:5], -1, 0
	v_readlane_b32 s9, v252, 57
	s_and_b64 s[8:9], s[8:9], s[4:5]
	s_mulk_i32 s6, 0xfe80
	v_cndmask_b32_e64 v0, 0, 1, s[8:9]
	v_cmp_ne_u32_e64 s[4:5], 1, v0
	s_andn2_b64 vcc, exec, s[8:9]
	s_barrier
	s_cbranch_vccnz .LBB0_707
	s_ashr_i32 s1, s0, 31
	v_lshl_add_u64 v[12:13], s[0:1], 2, v[4:5]
	s_add_i32 s1, s6, s3
	v_add_u32_e32 v0, s1, v9
	v_ashrrev_i32_e32 v1, 31, v0
	v_lshlrev_b64 v[0:1], 11, v[0:1]
	v_lshl_add_u64 v[0:1], v[12:13], 0, v[0:1]
	global_load_dwordx4 v[0:3], v[0:1], off
	v_add_u32_e32 v64, s1, v8
	v_ashrrev_i32_e32 v65, 31, v64
	v_lshlrev_b64 v[64:65], 11, v[64:65]
	v_lshl_add_u64 v[64:65], v[12:13], 0, v[64:65]
	global_load_dwordx4 v[64:67], v[64:65], off
	s_waitcnt vmcnt(1)
	v_cvt_pk_bf16_f32 v0, v0, s0
	ds_write_b16 v10, v0
	v_cvt_pk_bf16_f32 v0, v1, s0
	ds_write_b16 v10, v0 offset:132
	v_cvt_pk_bf16_f32 v0, v2, s0
	ds_write_b16 v10, v0 offset:264
	v_cvt_pk_bf16_f32 v0, v3, s0
	ds_write_b16 v10, v0 offset:396
	s_waitcnt vmcnt(0)
	v_cvt_pk_bf16_f32 v0, v64, s0
	ds_write_b16 v11, v0
	v_cvt_pk_bf16_f32 v0, v65, s0
	ds_write_b16 v11, v0 offset:132
	v_cvt_pk_bf16_f32 v0, v66, s0
	ds_write_b16 v11, v0 offset:264
	v_cvt_pk_bf16_f32 v0, v67, s0
	ds_write_b16 v11, v0 offset:396

; __device__ __forceinline__ unsigned short f2bf(float f) { return (unsigned short)(pk2(f, 0.f) & 0xffffu); }
; __device__ __forceinline__ void cvt_tile(unsigned char* lds, const float* src, int ld, int n_begin, int K, bf16_t* dst, int Kd, int koff, int mode, int roff, int t, int tid) {
;     const int ntk = Kd / 64; unsigned short* tile = (unsigned short*)lds;
;     const int tn = t / ntk, tk = t - tn * ntk; const int n0 = tn * 64, k0 = tk * 64;
;     const bool valid = (src != nullptr) && (k0 >= koff) && (k0 < koff + K);
;     __syncthreads();
;     if (valid) {
; #pragma unroll
;         for (int it = 0; it < 2; ++it) { const int idx = tid + 512 * it, kr = idx >> 4, nc4 = idx & 15;
;             const f32x4 v = *(const f32x4*)(src + (size_t)(k0 - koff + kr) * ld + n_begin + n0 + 4 * nc4);
; #pragma unroll
;             for (int j = 0; j < 4; ++j) tile[(4 * nc4 + j) * 66 + kr] = f2bf(v[j]); }
;     }
.LBB0_712:
	s_ashr_i32 s4, s2, 31
	s_lshr_b32 s4, s4, 28
	s_add_i32 s4, s2, s4
	s_ashr_i32 s4, s4, 4
	s_lshl_b32 s9, s4, 10
	s_lshl_b32 s10, s4, 6
	s_sub_i32 s8, s3, s9
	s_cmpk_lt_u32 s8, 0x200
	v_readlane_b32 s12, v252, 58
	s_cselect_b64 s[4:5], -1, 0
	v_readlane_b32 s13, v252, 59
	s_and_b64 s[12:13], s[12:13], s[4:5]
	s_andn2_b64 vcc, exec, s[12:13]
	v_cndmask_b32_e64 v0, 0, 1, s[12:13]
	v_cmp_ne_u32_e64 s[4:5], 1, v0
	s_barrier
	s_cbranch_vccnz .LBB0_714
	s_sub_i32 s9, 0, s9
	s_add_i32 s9, s9, s3
	v_add_u32_e32 v0, s9, v6
	s_ashr_i32 s11, s10, 31
	v_ashrrev_i32_e32 v1, 31, v0
	v_lshl_add_u64 v[12:13], s[10:11], 2, v[4:5]
	v_lshlrev_b64 v[0:1], 12, v[0:1]
	v_lshl_add_u64 v[0:1], v[12:13], 0, v[0:1]
	global_load_dwordx4 v[0:3], v[0:1], off
	v_add_u32_e32 v64, s9, v7
	v_ashrrev_i32_e32 v65, 31, v64
	v_lshlrev_b64 v[64:65], 12, v[64:65]
	v_lshl_add_u64 v[64:65], v[12:13], 0, v[64:65]
	global_load_dwordx4 v[64:67], v[64:65], off
	s_waitcnt vmcnt(1)
	v_cvt_pk_bf16_f32 v0, v0, s0
	ds_write_b16 v10, v0
	v_cvt_pk_bf16_f32 v0, v1, s0
	ds_write_b16 v10, v0 offset:132
	v_cvt_pk_bf16_f32 v0, v2, s0
	ds_write_b16 v10, v0 offset:264
	v_cvt_pk_bf16_f32 v0, v3, s0
	ds_write_b16 v10, v0 offset:396
	s_waitcnt vmcnt(0)
	v_cvt_pk_bf16_f32 v0, v64, s0
	ds_write_b16 v11, v0
	v_cvt_pk_bf16_f32 v0, v65, s0
	ds_write_b16 v11, v0 offset:132
	v_cvt_pk_bf16_f32 v0, v66, s0
	ds_write_b16 v11, v0 offset:264
	v_cvt_pk_bf16_f32 v0, v67, s0
	ds_write_b16 v11, v0 offset:396

; __device__ __forceinline__ unsigned short f2bf(float f) { return (unsigned short)(pk2(f, 0.f) & 0xffffu); }
; __device__ __forceinline__ void cvt_tile(unsigned char* lds, const float* src, int ld, int n_begin, int K, bf16_t* dst, int Kd, int koff, int mode, int roff, int t, int tid) {
;     const int ntk = Kd / 64; unsigned short* tile = (unsigned short*)lds;
;     const int tn = t / ntk, tk = t - tn * ntk; const int n0 = tn * 64, k0 = tk * 64;
;     const bool valid = (src != nullptr) && (k0 >= koff) && (k0 < koff + K);
;     __syncthreads();
;     if (valid) {
; #pragma unroll
;         for (int it = 0; it < 2; ++it) { const int idx = tid + 512 * it, kr = idx >> 4, nc4 = idx & 15;
;             const f32x4 v = *(const f32x4*)(src + (size_t)(k0 - koff + kr) * ld + n_begin + n0 + 4 * nc4);
; #pragma unroll
;             for (int j = 0; j < 4; ++j) tile[(4 * nc4 + j) * 66 + kr] = f2bf(v[j]); }
;     }
.LBB0_719:
	s_ashr_i32 s4, s2, 31
	s_lshr_b32 s4, s4, 28
	s_add_i32 s4, s2, s4
	s_ashr_i32 s4, s4, 4
	s_lshl_b32 s5, s4, 10
	s_lshl_b32 s6, s4, 6
	s_sub_i32 s4, s3, s5
	s_and_b32 s7, s4, 0xfffffe00
	s_cmpk_eq_i32 s7, 0x200
	s_cselect_b64 s[8:9], -1, 0
	s_cmpk_lg_i32 s7, 0x200
	s_barrier
	s_cbranch_scc1 .LBB0_721
	s_sub_i32 s5, 0, s5
	s_add_i32 s5, s5, s3
	v_add_u32_e32 v0, s5, v9
	s_ashr_i32 s7, s6, 31
	v_ashrrev_i32_e32 v1, 31, v0
	v_lshl_add_u64 v[12:13], s[6:7], 2, v[4:5]
	v_lshlrev_b64 v[0:1], 12, v[0:1]
	v_lshl_add_u64 v[0:1], v[12:13], 0, v[0:1]
	global_load_dwordx4 v[0:3], v[0:1], off
	v_add_u32_e32 v64, s5, v8
	v_ashrrev_i32_e32 v65, 31, v64
	v_lshlrev_b64 v[64:65], 12, v[64:65]
	v_lshl_add_u64 v[64:65], v[12:13], 0, v[64:65]
	global_load_dwordx4 v[64:67], v[64:65], off
	s_waitcnt vmcnt(1)
	v_cvt_pk_bf16_f32 v0, v0, s0
	ds_write_b16 v10, v0
	v_cvt_pk_bf16_f32 v0, v1, s0
	ds_write_b16 v10, v0 offset:132
	v_cvt_pk_bf16_f32 v0, v2, s0
	ds_write_b16 v10, v0 offset:264
	v_cvt_pk_bf16_f32 v0, v3, s0
	ds_write_b16 v10, v0 offset:396
	s_waitcnt vmcnt(0)
	v_cvt_pk_bf16_f32 v0, v64, s0
	ds_write_b16 v11, v0
	v_cvt_pk_bf16_f32 v0, v65, s0
	ds_write_b16 v11, v0 offset:132
	v_cvt_pk_bf16_f32 v0, v66, s0
	ds_write_b16 v11, v0 offset:264
	v_cvt_pk_bf16_f32 v0, v67, s0
	ds_write_b16 v11, v0 offset:396

; __device__ __forceinline__ unsigned short f2bf(float f) { return (unsigned short)(pk2(f, 0.f) & 0xffffu); }
; __device__ __forceinline__ void cvt_tile(unsigned char* lds, const float* src, int ld, int n_begin, int K, bf16_t* dst, int Kd, int koff, int mode, int roff, int t, int tid) {
;     const int ntk = Kd / 64; unsigned short* tile = (unsigned short*)lds;
;     const int tn = t / ntk, tk = t - tn * ntk; const int n0 = tn * 64, k0 = tk * 64;
;     const bool valid = (src != nullptr) && (k0 >= koff) && (k0 < koff + K);
;     __syncthreads();
;     if (valid) {
; #pragma unroll
;         for (int it = 0; it < 2; ++it) { const int idx = tid + 512 * it, kr = idx >> 4, nc4 = idx & 15;
;             const f32x4 v = *(const f32x4*)(src + (size_t)(k0 - koff + kr) * ld + n_begin + n0 + 4 * nc4);
; #pragma unroll
;             for (int j = 0; j < 4; ++j) tile[(4 * nc4 + j) * 66 + kr] = f2bf(v[j]); }
;     }
.LBB0_726:
	s_ashr_i32 s0, s2, 31
	s_lshr_b32 s0, s0, 28
	s_add_i32 s0, s2, s0
	s_ashr_i32 s0, s0, 4
	s_lshl_b32 s1, s0, 10
	s_lshl_b32 s6, s0, 6
	s_sub_i32 s0, s3, s1
	s_cmpk_lt_u32 s0, 0x400
	v_readlane_b32 s8, v253, 12
	s_cselect_b64 s[4:5], -1, 0
	v_readlane_b32 s9, v253, 13
	s_and_b64 s[8:9], s[8:9], s[4:5]
	s_andn2_b64 vcc, exec, s[8:9]
	v_cndmask_b32_e64 v0, 0, 1, s[8:9]
	v_cmp_ne_u32_e64 s[4:5], 1, v0
	s_barrier
	s_cbranch_vccnz .LBB0_728
	s_sub_i32 s1, 0, s1
	s_add_i32 s1, s1, s3
	v_add_u32_e32 v0, s1, v6
	s_ashr_i32 s7, s6, 31
	v_ashrrev_i32_e32 v1, 31, v0
	v_lshl_add_u64 v[12:13], s[6:7], 2, v[4:5]
	v_lshlrev_b64 v[0:1], 12, v[0:1]
	v_lshl_add_u64 v[0:1], v[12:13], 0, v[0:1]
	global_load_dwordx4 v[0:3], v[0:1], off
	v_add_u32_e32 v64, s1, v7
	v_ashrrev_i32_e32 v65, 31, v64
	v_lshlrev_b64 v[64:65], 12, v[64:65]
	v_lshl_add_u64 v[64:65], v[12:13], 0, v[64:65]
	global_load_dwordx4 v[64:67], v[64:65], off
	s_waitcnt vmcnt(1)
	v_cvt_pk_bf16_f32 v0, v0, s0
	ds_write_b16 v10, v0
	v_cvt_pk_bf16_f32 v0, v1, s0
	ds_write_b16 v10, v0 offset:132
	v_cvt_pk_bf16_f32 v0, v2, s0
	ds_write_b16 v10, v0 offset:264
	v_cvt_pk_bf16_f32 v0, v3, s0
	ds_write_b16 v10, v0 offset:396
	s_waitcnt vmcnt(0)
	v_cvt_pk_bf16_f32 v0, v64, s0
	ds_write_b16 v11, v0
	v_cvt_pk_bf16_f32 v0, v65, s0
	ds_write_b16 v11, v0 offset:132
	v_cvt_pk_bf16_f32 v0, v66, s0
	ds_write_b16 v11, v0 offset:264
	v_cvt_pk_bf16_f32 v0, v67, s0
	ds_write_b16 v11, v0 offset:396
